# last-layer gate epilogue (f32 output variant) rewritten with batched loads like the bf16 one
# baseline (speedup 1.0000x reference)
.LBB0_665:
	s_add_u32 s1, s40, 0xfff80080
	s_addc_u32 s2, s41, -1
	s_add_i32 s3, 0, 0x10000
	v_add_u32_e32 v138, s3, v141
	ds_read_b128 v[134:137], v138
	ds_read_b128 v[142:145], v138 offset:1024
	ds_read_b128 v[150:153], v138 offset:2048
	ds_read_b128 v[154:157], v138 offset:3072
	s_cmp_eq_u32 s90, 28
	s_cselect_b32 s75, s47, s2
	s_cselect_b32 s74, s53, s1
	s_cselect_b32 s73, s45, s89
	s_cselect_b32 s72, s60, s61
	v_lshl_add_u64 v[138:139], s[40:41], 0, v[130:131]
	s_add_i32 m0, s79, 0xc000
	ds_read_b128 v[158:161], v149
	ds_read_b128 v[162:165], v149 offset:1024
	ds_read_b128 v[166:169], v149 offset:2048
	ds_read_b128 v[170:173], v149 offset:3072
	ds_read_b128 v[182:185], v149 offset:4096
	ds_read_b128 v[200:203], v149 offset:5120
	ds_read_b128 v[208:211], v149 offset:6144
	ds_read_b128 v[212:215], v149 offset:7168
	global_load_lds_dwordx4 v[138:139], off
	v_lshl_add_u64 v[138:139], s[40:41], 0, v[132:133]
	s_add_i32 m0, s79, 0xe000
	s_nop 0
	global_load_lds_dwordx4 v[138:139], off
	s_waitcnt lgkmcnt(8)
	s_barrier
	s_waitcnt lgkmcnt(0)
	s_setprio 1
	s_waitcnt lgkmcnt(0)
	v_mfma_f32_16x16x32_bf16 v[124:127], v[134:137], v[158:161], v[124:127]
	v_mfma_f32_16x16x32_bf16 v[120:123], v[150:153], v[158:161], v[120:123]
	v_mfma_f32_16x16x32_bf16 v[108:111], v[134:137], v[166:169], v[108:111]
	v_mfma_f32_16x16x32_bf16 v[104:107], v[150:153], v[166:169], v[104:107]
	v_mfma_f32_16x16x32_bf16 v[92:95], v[134:137], v[182:185], v[92:95]
	v_mfma_f32_16x16x32_bf16 v[88:91], v[150:153], v[182:185], v[88:91]
	v_mfma_f32_16x16x32_bf16 v[76:79], v[134:137], v[208:211], v[76:79]
	v_mfma_f32_16x16x32_bf16 v[72:75], v[150:153], v[208:211], v[72:75]
	v_mfma_f32_16x16x32_bf16 v[124:127], v[142:145], v[162:165], v[124:127]
	v_mfma_f32_16x16x32_bf16 v[120:123], v[154:157], v[162:165], v[120:123]
	v_mfma_f32_16x16x32_bf16 v[108:111], v[142:145], v[170:173], v[108:111]
	v_mfma_f32_16x16x32_bf16 v[104:107], v[154:157], v[170:173], v[104:107]
	v_mfma_f32_16x16x32_bf16 v[92:95], v[142:145], v[200:203], v[92:95]
	v_mfma_f32_16x16x32_bf16 v[88:91], v[154:157], v[200:203], v[88:91]
	v_mfma_f32_16x16x32_bf16 v[76:79], v[142:145], v[212:215], v[76:79]
	v_mfma_f32_16x16x32_bf16 v[72:75], v[154:157], v[212:215], v[72:75]
	s_setprio 0
	s_barrier
	s_add_i32 s1, 0, 0x14000
	v_add_u32_e32 v138, s1, v141
	s_add_i32 s2, s3, s78
	ds_read_b128 v[216:219], v138
	ds_read_b128 v[220:223], v138 offset:1024
	ds_read_b128 v[224:227], v138 offset:2048
	ds_read_b128 v[228:231], v138 offset:3072
	v_lshl_add_u64 v[138:139], s[72:73], 0, v[176:177]
	s_mov_b32 m0, s2
	v_lshl_add_u64 v[174:175], s[72:73], 0, v[128:129]
	global_load_lds_dwordx4 v[138:139], off
	s_add_i32 m0, s2, 0x2000
	s_nop 0
	global_load_lds_dwordx4 v[174:175], off
	s_barrier
	s_waitcnt lgkmcnt(0)
	s_setprio 1
	s_waitcnt lgkmcnt(0)
	v_mfma_f32_16x16x32_bf16 v[116:119], v[216:219], v[158:161], v[116:119]
	v_mfma_f32_16x16x32_bf16 v[112:115], v[224:227], v[158:161], v[112:115]
	v_mfma_f32_16x16x32_bf16 v[100:103], v[216:219], v[166:169], v[100:103]
	v_mfma_f32_16x16x32_bf16 v[96:99], v[224:227], v[166:169], v[96:99]
	v_mfma_f32_16x16x32_bf16 v[84:87], v[216:219], v[182:185], v[84:87]
	v_mfma_f32_16x16x32_bf16 v[80:83], v[224:227], v[182:185], v[80:83]
	v_mfma_f32_16x16x32_bf16 v[68:71], v[216:219], v[208:211], v[68:71]
	v_mfma_f32_16x16x32_bf16 v[64:67], v[224:227], v[208:211], v[64:67]
	v_mfma_f32_16x16x32_bf16 v[116:119], v[220:223], v[162:165], v[116:119]
	v_mfma_f32_16x16x32_bf16 v[112:115], v[228:231], v[162:165], v[112:115]
	v_mfma_f32_16x16x32_bf16 v[100:103], v[220:223], v[170:173], v[100:103]
	v_mfma_f32_16x16x32_bf16 v[96:99], v[228:231], v[170:173], v[96:99]
	v_mfma_f32_16x16x32_bf16 v[84:87], v[220:223], v[200:203], v[84:87]
	v_mfma_f32_16x16x32_bf16 v[80:83], v[228:231], v[200:203], v[80:83]
	v_mfma_f32_16x16x32_bf16 v[68:71], v[220:223], v[212:215], v[68:71]
	v_mfma_f32_16x16x32_bf16 v[64:67], v[228:231], v[212:215], v[64:67]
	s_setprio 0
	s_mov_b32 m0, s79
	v_lshl_add_u64 v[186:187], s[74:75], 0, v[176:177]
	s_barrier
	ds_read_b128 v[158:161], v149 offset:16384
	ds_read_b128 v[162:165], v149 offset:17408
	ds_read_b128 v[166:169], v149 offset:18432
	ds_read_b128 v[170:173], v149 offset:19456
	ds_read_b128 v[182:185], v149 offset:20480
	ds_read_b128 v[200:203], v149 offset:21504
	ds_read_b128 v[208:211], v149 offset:22528
	ds_read_b128 v[212:215], v149 offset:23552
	global_load_lds_dwordx4 v[186:187], off
	v_lshl_add_u64 v[190:191], s[74:75], 0, v[128:129]
	s_mov_b32 m0, s80
	s_nop 0
	global_load_lds_dwordx4 v[190:191], off
	s_barrier
	s_waitcnt lgkmcnt(0)
	s_setprio 1
	s_waitcnt lgkmcnt(0)
	v_mfma_f32_16x16x32_bf16 v[60:63], v[134:137], v[158:161], v[60:63]
	v_mfma_f32_16x16x32_bf16 v[56:59], v[150:153], v[158:161], v[56:59]
	v_mfma_f32_16x16x32_bf16 v[44:47], v[134:137], v[166:169], v[44:47]
	v_mfma_f32_16x16x32_bf16 v[40:43], v[150:153], v[166:169], v[40:43]
	v_mfma_f32_16x16x32_bf16 v[28:31], v[134:137], v[182:185], v[28:31]
	v_mfma_f32_16x16x32_bf16 v[24:27], v[150:153], v[182:185], v[24:27]
	v_mfma_f32_16x16x32_bf16 v[12:15], v[134:137], v[208:211], v[12:15]
	v_mfma_f32_16x16x32_bf16 v[8:11], v[150:153], v[208:211], v[8:11]
	v_mfma_f32_16x16x32_bf16 v[60:63], v[142:145], v[162:165], v[60:63]
	v_mfma_f32_16x16x32_bf16 v[56:59], v[154:157], v[162:165], v[56:59]
	v_mfma_f32_16x16x32_bf16 v[44:47], v[142:145], v[170:173], v[44:47]
	v_mfma_f32_16x16x32_bf16 v[40:43], v[154:157], v[170:173], v[40:43]
	v_mfma_f32_16x16x32_bf16 v[28:31], v[142:145], v[200:203], v[28:31]
	v_mfma_f32_16x16x32_bf16 v[24:27], v[154:157], v[200:203], v[24:27]
	v_mfma_f32_16x16x32_bf16 v[12:15], v[142:145], v[212:215], v[12:15]
	v_mfma_f32_16x16x32_bf16 v[8:11], v[154:157], v[212:215], v[8:11]
	s_setprio 0
	s_barrier
	s_add_u32 s2, s72, 0x80000
	s_addc_u32 s3, s73, 0
	s_add_i32 s1, s1, s78
	v_lshl_add_u64 v[134:135], s[2:3], 0, v[176:177]
	s_mov_b32 m0, s1
	s_nop 0
	global_load_lds_dwordx4 v[134:135], off
	v_lshl_add_u64 v[134:135], s[2:3], 0, v[128:129]
	s_add_i32 m0, s1, 0x2000
	s_nop 0
	global_load_lds_dwordx4 v[134:135], off
	s_waitcnt vmcnt(6)
	s_barrier
	s_setprio 1
	v_mfma_f32_16x16x32_bf16 v[52:55], v[216:219], v[158:161], v[52:55]
	v_mfma_f32_16x16x32_bf16 v[48:51], v[224:227], v[158:161], v[48:51]
	v_mfma_f32_16x16x32_bf16 v[36:39], v[216:219], v[166:169], v[36:39]
	v_mfma_f32_16x16x32_bf16 v[32:35], v[224:227], v[166:169], v[32:35]
	v_mfma_f32_16x16x32_bf16 v[20:23], v[216:219], v[182:185], v[20:23]
	v_mfma_f32_16x16x32_bf16 v[16:19], v[224:227], v[182:185], v[16:19]
	v_mfma_f32_16x16x32_bf16 v[4:7], v[216:219], v[208:211], v[4:7]
	v_mfma_f32_16x16x32_bf16 v[0:3], v[224:227], v[208:211], v[0:3]
	v_mfma_f32_16x16x32_bf16 v[52:55], v[220:223], v[162:165], v[52:55]
	v_mfma_f32_16x16x32_bf16 v[48:51], v[228:231], v[162:165], v[48:51]
	v_mfma_f32_16x16x32_bf16 v[36:39], v[220:223], v[170:173], v[36:39]
	v_mfma_f32_16x16x32_bf16 v[32:35], v[228:231], v[170:173], v[32:35]
	v_mfma_f32_16x16x32_bf16 v[20:23], v[220:223], v[200:203], v[20:23]
	v_mfma_f32_16x16x32_bf16 v[16:19], v[228:231], v[200:203], v[16:19]
	v_mfma_f32_16x16x32_bf16 v[4:7], v[220:223], v[212:215], v[4:7]
	v_mfma_f32_16x16x32_bf16 v[0:3], v[228:231], v[212:215], v[0:3]
	s_setprio 0
	s_add_i32 s1, 0, 0x18000
	v_add_u32_e32 v140, s1, v141
	s_barrier
	ds_read_b128 v[134:137], v140
	ds_read_b128 v[142:145], v140 offset:1024
	ds_read_b128 v[150:153], v140 offset:2048
	ds_read_b128 v[154:157], v140 offset:3072
	s_add_u32 s2, s74, 0x80000
	s_addc_u32 s3, s75, 0
	s_mov_b32 m0, s81
	v_lshl_add_u64 v[194:195], s[2:3], 0, v[176:177]
	ds_read_b128 v[158:161], v149 offset:32768
	ds_read_b128 v[162:165], v149 offset:33792
	ds_read_b128 v[166:169], v149 offset:34816
	ds_read_b128 v[170:173], v149 offset:35840
	ds_read_b128 v[182:185], v149 offset:36864
	ds_read_b128 v[200:203], v149 offset:37888
	ds_read_b128 v[208:211], v149 offset:38912
	ds_read_b128 v[212:215], v149 offset:39936
	global_load_lds_dwordx4 v[194:195], off
	v_lshl_add_u64 v[194:195], s[2:3], 0, v[128:129]
	s_mov_b32 m0, s82
	s_nop 0
	global_load_lds_dwordx4 v[194:195], off
	s_waitcnt lgkmcnt(8)
	s_barrier
	s_waitcnt lgkmcnt(0)
	s_setprio 1
	s_waitcnt lgkmcnt(0)
	v_mfma_f32_16x16x32_bf16 v[124:127], v[134:137], v[158:161], v[124:127]
	v_mfma_f32_16x16x32_bf16 v[120:123], v[150:153], v[158:161], v[120:123]
	v_mfma_f32_16x16x32_bf16 v[108:111], v[134:137], v[166:169], v[108:111]
	v_mfma_f32_16x16x32_bf16 v[104:107], v[150:153], v[166:169], v[104:107]
	v_mfma_f32_16x16x32_bf16 v[92:95], v[134:137], v[182:185], v[92:95]
	v_mfma_f32_16x16x32_bf16 v[88:91], v[150:153], v[182:185], v[88:91]
	v_mfma_f32_16x16x32_bf16 v[76:79], v[134:137], v[208:211], v[76:79]
	v_mfma_f32_16x16x32_bf16 v[72:75], v[150:153], v[208:211], v[72:75]
	v_mfma_f32_16x16x32_bf16 v[124:127], v[142:145], v[162:165], v[124:127]
	v_mfma_f32_16x16x32_bf16 v[120:123], v[154:157], v[162:165], v[120:123]
	v_mfma_f32_16x16x32_bf16 v[108:111], v[142:145], v[170:173], v[108:111]
	v_mfma_f32_16x16x32_bf16 v[104:107], v[154:157], v[170:173], v[104:107]
	v_mfma_f32_16x16x32_bf16 v[92:95], v[142:145], v[200:203], v[92:95]
	v_mfma_f32_16x16x32_bf16 v[88:91], v[154:157], v[200:203], v[88:91]
	v_mfma_f32_16x16x32_bf16 v[76:79], v[142:145], v[212:215], v[76:79]
	v_mfma_f32_16x16x32_bf16 v[72:75], v[154:157], v[212:215], v[72:75]
	s_setprio 0
	s_barrier
	s_add_i32 s12, 0, 0x1c000
	s_add_i32 s1, s1, s78
	v_add_u32_e32 v140, s12, v141
	v_lshl_add_u64 v[138:139], v[138:139], 0, s[20:21]
	s_mov_b32 m0, s1
	ds_read_b128 v[216:219], v140
	ds_read_b128 v[220:223], v140 offset:1024
	ds_read_b128 v[224:227], v140 offset:2048
	ds_read_b128 v[228:231], v140 offset:3072
	global_load_lds_dwordx4 v[138:139], off
	v_lshl_add_u64 v[138:139], v[174:175], 0, s[20:21]
	s_add_i32 m0, s1, 0x2000
	s_nop 0
	global_load_lds_dwordx4 v[138:139], off
	s_barrier
	s_waitcnt lgkmcnt(0)
	s_setprio 1
	s_waitcnt lgkmcnt(0)
	v_mfma_f32_16x16x32_bf16 v[116:119], v[216:219], v[158:161], v[116:119]
	v_mfma_f32_16x16x32_bf16 v[112:115], v[224:227], v[158:161], v[112:115]
	v_mfma_f32_16x16x32_bf16 v[100:103], v[216:219], v[166:169], v[100:103]
	v_mfma_f32_16x16x32_bf16 v[96:99], v[224:227], v[166:169], v[96:99]
	v_mfma_f32_16x16x32_bf16 v[84:87], v[216:219], v[182:185], v[84:87]
	v_mfma_f32_16x16x32_bf16 v[80:83], v[224:227], v[182:185], v[80:83]
	v_mfma_f32_16x16x32_bf16 v[68:71], v[216:219], v[208:211], v[68:71]
	v_mfma_f32_16x16x32_bf16 v[64:67], v[224:227], v[208:211], v[64:67]
	v_mfma_f32_16x16x32_bf16 v[116:119], v[220:223], v[162:165], v[116:119]
	v_mfma_f32_16x16x32_bf16 v[112:115], v[228:231], v[162:165], v[112:115]
	v_mfma_f32_16x16x32_bf16 v[100:103], v[220:223], v[170:173], v[100:103]
	v_mfma_f32_16x16x32_bf16 v[96:99], v[228:231], v[170:173], v[96:99]
	v_mfma_f32_16x16x32_bf16 v[84:87], v[220:223], v[200:203], v[84:87]
	v_mfma_f32_16x16x32_bf16 v[80:83], v[228:231], v[200:203], v[80:83]
	v_mfma_f32_16x16x32_bf16 v[68:71], v[220:223], v[212:215], v[68:71]
	v_mfma_f32_16x16x32_bf16 v[64:67], v[228:231], v[212:215], v[64:67]
	s_setprio 0
	s_mov_b32 m0, s87
	v_lshl_add_u64 v[138:139], v[186:187], 0, s[20:21]
	s_barrier
	ds_read_b128 v[158:161], v149 offset:49152
	ds_read_b128 v[162:165], v149 offset:50176
	ds_read_b128 v[166:169], v149 offset:51200
	ds_read_b128 v[170:173], v149 offset:52224
	ds_read_b128 v[182:185], v149 offset:53248
	ds_read_b128 v[200:203], v149 offset:54272
	ds_read_b128 v[208:211], v149 offset:55296
	ds_read_b128 v[212:215], v149 offset:56320
	global_load_lds_dwordx4 v[138:139], off
	v_lshl_add_u64 v[138:139], v[190:191], 0, s[20:21]
	s_mov_b32 m0, s77
	s_nop 0
	global_load_lds_dwordx4 v[138:139], off
	s_barrier
	s_waitcnt lgkmcnt(0)
	s_setprio 1
	s_waitcnt lgkmcnt(0)
	v_mfma_f32_16x16x32_bf16 v[60:63], v[134:137], v[158:161], v[60:63]
	v_mfma_f32_16x16x32_bf16 v[56:59], v[150:153], v[158:161], v[56:59]
	v_mfma_f32_16x16x32_bf16 v[44:47], v[134:137], v[166:169], v[44:47]
	v_mfma_f32_16x16x32_bf16 v[40:43], v[150:153], v[166:169], v[40:43]
	v_mfma_f32_16x16x32_bf16 v[28:31], v[134:137], v[182:185], v[28:31]
	v_mfma_f32_16x16x32_bf16 v[24:27], v[150:153], v[182:185], v[24:27]
	v_mfma_f32_16x16x32_bf16 v[12:15], v[134:137], v[208:211], v[12:15]
	v_mfma_f32_16x16x32_bf16 v[8:11], v[150:153], v[208:211], v[8:11]
	v_mfma_f32_16x16x32_bf16 v[60:63], v[142:145], v[162:165], v[60:63]
	v_mfma_f32_16x16x32_bf16 v[56:59], v[154:157], v[162:165], v[56:59]
	v_mfma_f32_16x16x32_bf16 v[44:47], v[142:145], v[170:173], v[44:47]
	v_mfma_f32_16x16x32_bf16 v[40:43], v[154:157], v[170:173], v[40:43]
	v_mfma_f32_16x16x32_bf16 v[28:31], v[142:145], v[200:203], v[28:31]
	v_mfma_f32_16x16x32_bf16 v[24:27], v[154:157], v[200:203], v[24:27]
	v_mfma_f32_16x16x32_bf16 v[12:15], v[142:145], v[212:215], v[12:15]
	v_mfma_f32_16x16x32_bf16 v[8:11], v[154:157], v[212:215], v[8:11]
	s_setprio 0
	s_barrier
	s_add_u32 s2, s72, 0x80080
	s_addc_u32 s3, s73, 0
	s_add_i32 s1, s12, s78
	v_lshl_add_u64 v[134:135], s[2:3], 0, v[176:177]
	s_mov_b32 m0, s1
	s_nop 0
	global_load_lds_dwordx4 v[134:135], off
	v_lshl_add_u64 v[134:135], s[2:3], 0, v[128:129]
	s_add_i32 m0, s1, 0x2000
	s_nop 0
	global_load_lds_dwordx4 v[134:135], off
	s_waitcnt vmcnt(6)
	s_barrier
	s_setprio 1
	v_mfma_f32_16x16x32_bf16 v[52:55], v[216:219], v[158:161], v[52:55]
	v_mfma_f32_16x16x32_bf16 v[48:51], v[224:227], v[158:161], v[48:51]
	v_mfma_f32_16x16x32_bf16 v[36:39], v[216:219], v[166:169], v[36:39]
	v_mfma_f32_16x16x32_bf16 v[32:35], v[224:227], v[166:169], v[32:35]
	v_mfma_f32_16x16x32_bf16 v[20:23], v[216:219], v[182:185], v[20:23]
	v_mfma_f32_16x16x32_bf16 v[16:19], v[224:227], v[182:185], v[16:19]
	v_mfma_f32_16x16x32_bf16 v[4:7], v[216:219], v[208:211], v[4:7]
	v_mfma_f32_16x16x32_bf16 v[0:3], v[224:227], v[208:211], v[0:3]
	v_mfma_f32_16x16x32_bf16 v[52:55], v[220:223], v[162:165], v[52:55]
	v_mfma_f32_16x16x32_bf16 v[48:51], v[228:231], v[162:165], v[48:51]
	v_mfma_f32_16x16x32_bf16 v[36:39], v[220:223], v[170:173], v[36:39]
	v_mfma_f32_16x16x32_bf16 v[32:35], v[228:231], v[170:173], v[32:35]
	v_mfma_f32_16x16x32_bf16 v[20:23], v[220:223], v[200:203], v[20:23]
	v_mfma_f32_16x16x32_bf16 v[16:19], v[228:231], v[200:203], v[16:19]
	v_mfma_f32_16x16x32_bf16 v[4:7], v[220:223], v[212:215], v[4:7]
	v_mfma_f32_16x16x32_bf16 v[0:3], v[228:231], v[212:215], v[0:3]
	s_setprio 0
	s_add_i32 s90, s90, 2
	s_add_u32 s40, s40, 0x100
	s_addc_u32 s41, s41, 0
	s_add_u32 s61, s61, 0x100
	s_addc_u32 s89, s89, 0
	s_cmp_gt_u32 s90, 29
	s_barrier
	s_cbranch_scc0 .LBB0_665
	v_and_b32_e32 v198, 15, v147
	v_ashrrev_i32_e32 v252, 4, v147
	s_lshl_b32 s1, s52, 8
	s_add_i32 s1, s1, s83
	v_or_b32_e32 v198, s1, v198
	s_lshl_b32 s1, s49, 8
	s_or_b32 s1, s1, s86
	v_lshl_add_u32 v140, v252, 2, s1
	v_lshl_add_u32 v140, v198, 11, v140
	v_lshlrev_b32_e32 v140, 1, v140
	v_lshlrev_b32_e32 v146, 5, v252
	v_lshl_add_u32 v146, v198, 7, v146
	v_readlane_b32 s90, v255, 23
	v_readlane_b32 s30, v255, 27
	s_mov_b32 s49, s44
	s_mov_b32 s52, s46
	s_mov_b64 s[72:73], s[70:71]
	v_readlane_b32 s91, v255, 24
	v_readlane_b32 s31, v255, 28
	s_mov_b64 s[40:41], s[68:69]
	v_mov_b32_e32 v148, v146
	global_load_dwordx4 v[208:211], v148, s[16:17]
	global_load_dwordx4 v[212:215], v148, s[16:17] offset:16
	v_add_u32_e32 v188, 0x800, v146
	global_load_dwordx4 v[216:219], v188, s[16:17]
	global_load_dwordx4 v[220:223], v188, s[16:17] offset:16
	v_add_u32_e32 v192, 0x1000, v146
	global_load_dwordx4 v[224:227], v192, s[16:17]
	global_load_dwordx4 v[228:231], v192, s[16:17] offset:16
	v_add_u32_e32 v196, 0x1800, v146
	global_load_dwordx4 v[232:235], v196, s[16:17]
	global_load_dwordx4 v[236:239], v196, s[16:17] offset:16
	v_mov_b32_e32 v148, v140
	global_load_dwordx2 v[152:153], v148, s[58:59] offset:0
	global_load_dwordx2 v[154:155], v148, s[56:57] offset:0
	global_load_dwordx2 v[156:157], v148, s[58:59] offset:32
	global_load_dwordx2 v[158:159], v148, s[56:57] offset:32
	global_load_dwordx2 v[160:161], v148, s[58:59] offset:256
	global_load_dwordx2 v[162:163], v148, s[56:57] offset:256
	global_load_dwordx2 v[164:165], v148, s[58:59] offset:288
	global_load_dwordx2 v[166:167], v148, s[56:57] offset:288
	v_add_u32_e32 v188, 0x10000, v140
	global_load_dwordx2 v[168:169], v188, s[58:59] offset:0
	global_load_dwordx2 v[170:171], v188, s[56:57] offset:0
	global_load_dwordx2 v[172:173], v188, s[58:59] offset:32
	global_load_dwordx2 v[174:175], v188, s[56:57] offset:32
	global_load_dwordx2 v[240:241], v188, s[58:59] offset:256
	global_load_dwordx2 v[242:243], v188, s[56:57] offset:256
	global_load_dwordx2 v[244:245], v188, s[58:59] offset:288
	global_load_dwordx2 v[246:247], v188, s[56:57] offset:288
	v_add_u32_e32 v192, 0x20000, v140
	global_load_dwordx2 v[182:183], v192, s[58:59] offset:0
	global_load_dwordx2 v[184:185], v192, s[56:57] offset:0
	global_load_dwordx2 v[186:187], v192, s[58:59] offset:32
	global_load_dwordx2 v[200:201], v192, s[56:57] offset:32
	global_load_dwordx2 v[202:203], v192, s[58:59] offset:256
	global_load_dwordx2 v[204:205], v192, s[56:57] offset:256
	global_load_dwordx2 v[134:135], v192, s[58:59] offset:288
	global_load_dwordx2 v[136:137], v192, s[56:57] offset:288
	v_add_u32_e32 v196, 0x30000, v140
	global_load_dwordx2 v[138:139], v196, s[58:59] offset:0
	global_load_dwordx2 v[142:143], v196, s[56:57] offset:0
	global_load_dwordx2 v[144:145], v196, s[58:59] offset:32
	global_load_dwordx2 v[190:191], v196, s[56:57] offset:32
	global_load_dwordx2 v[194:195], v196, s[58:59] offset:256
	global_load_dwordx2 v[248:249], v196, s[56:57] offset:256
	global_load_dwordx2 v[150:151], v196, s[58:59] offset:288
	s_waitcnt vmcnt(31)
	v_add_f32_e32 v208, v208, v209
	v_add_f32_e32 v210, v210, v211
	v_add_f32_e32 v212, v212, v213
	v_add_f32_e32 v214, v214, v215
	v_add_f32_e32 v208, v208, v210
	v_add_f32_e32 v212, v212, v214
	v_add_f32_e32 v208, v208, v212
	v_add_f32_e32 v216, v216, v217
	v_add_f32_e32 v218, v218, v219
	v_add_f32_e32 v220, v220, v221
	v_add_f32_e32 v222, v222, v223
	v_add_f32_e32 v216, v216, v218
	v_add_f32_e32 v220, v220, v222
	v_add_f32_e32 v216, v216, v220
	v_add_f32_e32 v224, v224, v225
	v_add_f32_e32 v226, v226, v227
	v_add_f32_e32 v228, v228, v229
	v_add_f32_e32 v230, v230, v231
	v_add_f32_e32 v224, v224, v226
	v_add_f32_e32 v228, v228, v230
	v_add_f32_e32 v224, v224, v228
	v_add_f32_e32 v232, v232, v233
	v_add_f32_e32 v234, v234, v235
	v_add_f32_e32 v236, v236, v237
	v_add_f32_e32 v238, v238, v239
	v_add_f32_e32 v232, v232, v234
	v_add_f32_e32 v236, v236, v238
	v_add_f32_e32 v232, v232, v236
	ds_bpermute_b32 v209, v207, v208
	ds_bpermute_b32 v217, v207, v216
	ds_bpermute_b32 v225, v207, v224
	ds_bpermute_b32 v233, v207, v232
	s_waitcnt lgkmcnt(0)
	v_add_f32_e32 v208, v208, v209
	v_add_f32_e32 v216, v216, v217
	v_add_f32_e32 v224, v224, v225
	v_add_f32_e32 v232, v232, v233
	ds_bpermute_b32 v209, v206, v208
	ds_bpermute_b32 v217, v206, v216
	ds_bpermute_b32 v225, v206, v224
	ds_bpermute_b32 v233, v206, v232
	s_waitcnt lgkmcnt(0)
	v_add_f32_e32 v208, v208, v209
	v_add_f32_e32 v216, v216, v217
	v_add_f32_e32 v224, v224, v225
	v_add_f32_e32 v232, v232, v233
	v_mul_f32_e32 v208, 0x3a000000, v208
	v_add_f32_e32 v208, 0x358637bd, v208
	v_mul_f32_e32 v216, 0x3a000000, v216
	v_add_f32_e32 v216, 0x358637bd, v216
	v_mul_f32_e32 v224, 0x3a000000, v224
	v_add_f32_e32 v224, 0x358637bd, v224
	v_mul_f32_e32 v232, 0x3a000000, v232
	v_add_f32_e32 v232, 0x358637bd, v232
	v_rsq_f32_e32 v208, v208
	v_rsq_f32_e32 v216, v216
	v_rsq_f32_e32 v224, v224
	v_rsq_f32_e32 v232, v232
	s_nop 0
	v_mov_b32_e32 v209, v216
	v_mov_b32_e32 v210, v224
	v_mov_b32_e32 v211, v232
	v_add_u32_e32 v148, 0x30000, v140
	global_load_dwordx2 v[238:239], v148, s[56:57] offset:288
	s_waitcnt vmcnt(16)
	v_mov_b32_e32 v188, v140
	v_mul_f32_e32 v124, v124, v208
	v_mul_f32_e32 v125, v125, v208
	v_mul_f32_e32 v126, v126, v208
	v_mul_f32_e32 v127, v127, v208
	v_mul_f32_e32 v124, 0xbfb8aa3b, v124
	v_mul_f32_e32 v125, 0xbfb8aa3b, v125
	v_mul_f32_e32 v126, 0xbfb8aa3b, v126
	v_mul_f32_e32 v127, 0xbfb8aa3b, v127
	v_exp_f32_e32 v124, v124
	v_exp_f32_e32 v125, v125
	v_exp_f32_e32 v126, v126
	v_exp_f32_e32 v127, v127
	v_add_f32_e32 v124, 1.0, v124
	v_add_f32_e32 v125, 1.0, v125
	v_add_f32_e32 v126, 1.0, v126
	v_add_f32_e32 v127, 1.0, v127
	v_rcp_f32_e32 v220, v124
	v_rcp_f32_e32 v221, v125
	v_rcp_f32_e32 v222, v126
	v_rcp_f32_e32 v223, v127
	v_fma_f32 v224, -v124, v220, 1.0
	v_fma_f32 v225, -v125, v221, 1.0
	v_fma_f32 v226, -v126, v222, 1.0
	v_fma_f32 v227, -v127, v223, 1.0
	v_fma_f32 v124, v224, v220, v220
	v_fma_f32 v125, v225, v221, v221
	v_fma_f32 v126, v226, v222, v222
	v_fma_f32 v127, v227, v223, v223
	v_lshlrev_b32_e32 v230, 16, v152
	v_and_b32_e32 v152, 0xffff0000, v152
	v_lshlrev_b32_e32 v231, 16, v153
	v_and_b32_e32 v153, 0xffff0000, v153
	v_lshlrev_b32_e32 v232, 16, v154
	v_and_b32_e32 v154, 0xffff0000, v154
	v_lshlrev_b32_e32 v233, 16, v155
	v_and_b32_e32 v155, 0xffff0000, v155
	v_fma_f32 v124, v124, v232, v230
	v_fma_f32 v125, v125, v154, v152
	v_fma_f32 v126, v126, v233, v231
	v_fma_f32 v127, v127, v155, v153
	v_lshlrev_b32_e32 v252, 1, v188
	global_store_dwordx4 v252, v[124:127], s[42:43] offset:0
	v_mul_f32_e32 v120, v120, v208
	v_mul_f32_e32 v121, v121, v208
	v_mul_f32_e32 v122, v122, v208
	v_mul_f32_e32 v123, v123, v208
	v_mul_f32_e32 v120, 0xbfb8aa3b, v120
	v_mul_f32_e32 v121, 0xbfb8aa3b, v121
	v_mul_f32_e32 v122, 0xbfb8aa3b, v122
	v_mul_f32_e32 v123, 0xbfb8aa3b, v123
	v_exp_f32_e32 v120, v120
	v_exp_f32_e32 v121, v121
	v_exp_f32_e32 v122, v122
	v_exp_f32_e32 v123, v123
	v_add_f32_e32 v120, 1.0, v120
	v_add_f32_e32 v121, 1.0, v121
	v_add_f32_e32 v122, 1.0, v122
	v_add_f32_e32 v123, 1.0, v123
	v_rcp_f32_e32 v220, v120
	v_rcp_f32_e32 v221, v121
	v_rcp_f32_e32 v222, v122
	v_rcp_f32_e32 v223, v123
	v_fma_f32 v224, -v120, v220, 1.0
	v_fma_f32 v225, -v121, v221, 1.0
	v_fma_f32 v226, -v122, v222, 1.0
	v_fma_f32 v227, -v123, v223, 1.0
	v_fma_f32 v120, v224, v220, v220
	v_fma_f32 v121, v225, v221, v221
	v_fma_f32 v122, v226, v222, v222
	v_fma_f32 v123, v227, v223, v223
	v_lshlrev_b32_e32 v230, 16, v156
	v_and_b32_e32 v156, 0xffff0000, v156
	v_lshlrev_b32_e32 v231, 16, v157
	v_and_b32_e32 v157, 0xffff0000, v157
	v_lshlrev_b32_e32 v232, 16, v158
	v_and_b32_e32 v158, 0xffff0000, v158
	v_lshlrev_b32_e32 v233, 16, v159
	v_and_b32_e32 v159, 0xffff0000, v159
	v_fma_f32 v120, v120, v232, v230
	v_fma_f32 v121, v121, v158, v156
	v_fma_f32 v122, v122, v233, v231
	v_fma_f32 v123, v123, v159, v157
	global_store_dwordx4 v252, v[120:123], s[42:43] offset:64
	v_mul_f32_e32 v116, v116, v208
	v_mul_f32_e32 v117, v117, v208
	v_mul_f32_e32 v118, v118, v208
	v_mul_f32_e32 v119, v119, v208
	v_mul_f32_e32 v116, 0xbfb8aa3b, v116
	v_mul_f32_e32 v117, 0xbfb8aa3b, v117
	v_mul_f32_e32 v118, 0xbfb8aa3b, v118
	v_mul_f32_e32 v119, 0xbfb8aa3b, v119
	v_exp_f32_e32 v116, v116
	v_exp_f32_e32 v117, v117
	v_exp_f32_e32 v118, v118
	v_exp_f32_e32 v119, v119
	v_add_f32_e32 v116, 1.0, v116
	v_add_f32_e32 v117, 1.0, v117
	v_add_f32_e32 v118, 1.0, v118
	v_add_f32_e32 v119, 1.0, v119
	v_rcp_f32_e32 v220, v116
	v_rcp_f32_e32 v221, v117
	v_rcp_f32_e32 v222, v118
	v_rcp_f32_e32 v223, v119
	v_fma_f32 v224, -v116, v220, 1.0
	v_fma_f32 v225, -v117, v221, 1.0
	v_fma_f32 v226, -v118, v222, 1.0
	v_fma_f32 v227, -v119, v223, 1.0
	v_fma_f32 v116, v224, v220, v220
	v_fma_f32 v117, v225, v221, v221
	v_fma_f32 v118, v226, v222, v222
	v_fma_f32 v119, v227, v223, v223
	v_lshlrev_b32_e32 v230, 16, v160
	v_and_b32_e32 v160, 0xffff0000, v160
	v_lshlrev_b32_e32 v231, 16, v161
	v_and_b32_e32 v161, 0xffff0000, v161
	v_lshlrev_b32_e32 v232, 16, v162
	v_and_b32_e32 v162, 0xffff0000, v162
	v_lshlrev_b32_e32 v233, 16, v163
	v_and_b32_e32 v163, 0xffff0000, v163
	v_fma_f32 v116, v116, v232, v230
	v_fma_f32 v117, v117, v162, v160
	v_fma_f32 v118, v118, v233, v231
	v_fma_f32 v119, v119, v163, v161
	global_store_dwordx4 v252, v[116:119], s[42:43] offset:512
	v_mul_f32_e32 v112, v112, v208
	v_mul_f32_e32 v113, v113, v208
	v_mul_f32_e32 v114, v114, v208
	v_mul_f32_e32 v115, v115, v208
	v_mul_f32_e32 v112, 0xbfb8aa3b, v112
	v_mul_f32_e32 v113, 0xbfb8aa3b, v113
	v_mul_f32_e32 v114, 0xbfb8aa3b, v114
	v_mul_f32_e32 v115, 0xbfb8aa3b, v115
	v_exp_f32_e32 v112, v112
	v_exp_f32_e32 v113, v113
	v_exp_f32_e32 v114, v114
	v_exp_f32_e32 v115, v115
	v_add_f32_e32 v112, 1.0, v112
	v_add_f32_e32 v113, 1.0, v113
	v_add_f32_e32 v114, 1.0, v114
	v_add_f32_e32 v115, 1.0, v115
	v_rcp_f32_e32 v220, v112
	v_rcp_f32_e32 v221, v113
	v_rcp_f32_e32 v222, v114
	v_rcp_f32_e32 v223, v115
	v_fma_f32 v224, -v112, v220, 1.0
	v_fma_f32 v225, -v113, v221, 1.0
	v_fma_f32 v226, -v114, v222, 1.0
	v_fma_f32 v227, -v115, v223, 1.0
	v_fma_f32 v112, v224, v220, v220
	v_fma_f32 v113, v225, v221, v221
	v_fma_f32 v114, v226, v222, v222
	v_fma_f32 v115, v227, v223, v223
	v_lshlrev_b32_e32 v230, 16, v164
	v_and_b32_e32 v164, 0xffff0000, v164
	v_lshlrev_b32_e32 v231, 16, v165
	v_and_b32_e32 v165, 0xffff0000, v165
	v_lshlrev_b32_e32 v232, 16, v166
	v_and_b32_e32 v166, 0xffff0000, v166
	v_lshlrev_b32_e32 v233, 16, v167
	v_and_b32_e32 v167, 0xffff0000, v167
	v_fma_f32 v112, v112, v232, v230
	v_fma_f32 v113, v113, v166, v164
	v_fma_f32 v114, v114, v233, v231
	v_fma_f32 v115, v115, v167, v165
	global_store_dwordx4 v252, v[112:115], s[42:43] offset:576
	v_add_u32_e32 v192, 0x10000, v140
	v_mul_f32_e32 v108, v108, v209
	v_mul_f32_e32 v109, v109, v209
	v_mul_f32_e32 v110, v110, v209
	v_mul_f32_e32 v111, v111, v209
	v_mul_f32_e32 v108, 0xbfb8aa3b, v108
	v_mul_f32_e32 v109, 0xbfb8aa3b, v109
	v_mul_f32_e32 v110, 0xbfb8aa3b, v110
	v_mul_f32_e32 v111, 0xbfb8aa3b, v111
	v_exp_f32_e32 v108, v108
	v_exp_f32_e32 v109, v109
	v_exp_f32_e32 v110, v110
	v_exp_f32_e32 v111, v111
	v_add_f32_e32 v108, 1.0, v108
	v_add_f32_e32 v109, 1.0, v109
	v_add_f32_e32 v110, 1.0, v110
	v_add_f32_e32 v111, 1.0, v111
	v_rcp_f32_e32 v220, v108
	v_rcp_f32_e32 v221, v109
	v_rcp_f32_e32 v222, v110
	v_rcp_f32_e32 v223, v111
	v_fma_f32 v224, -v108, v220, 1.0
	v_fma_f32 v225, -v109, v221, 1.0
	v_fma_f32 v226, -v110, v222, 1.0
	v_fma_f32 v227, -v111, v223, 1.0
	v_fma_f32 v108, v224, v220, v220
	v_fma_f32 v109, v225, v221, v221
	v_fma_f32 v110, v226, v222, v222
	v_fma_f32 v111, v227, v223, v223
	v_lshlrev_b32_e32 v230, 16, v168
	v_and_b32_e32 v168, 0xffff0000, v168
	v_lshlrev_b32_e32 v231, 16, v169
	v_and_b32_e32 v169, 0xffff0000, v169
	v_lshlrev_b32_e32 v232, 16, v170
	v_and_b32_e32 v170, 0xffff0000, v170
	v_lshlrev_b32_e32 v233, 16, v171
	v_and_b32_e32 v171, 0xffff0000, v171
	v_fma_f32 v108, v108, v232, v230
	v_fma_f32 v109, v109, v170, v168
	v_fma_f32 v110, v110, v233, v231
	v_fma_f32 v111, v111, v171, v169
	v_lshlrev_b32_e32 v252, 1, v192
	global_store_dwordx4 v252, v[108:111], s[42:43] offset:0
	v_mul_f32_e32 v104, v104, v209
	v_mul_f32_e32 v105, v105, v209
	v_mul_f32_e32 v106, v106, v209
	v_mul_f32_e32 v107, v107, v209
	v_mul_f32_e32 v104, 0xbfb8aa3b, v104
	v_mul_f32_e32 v105, 0xbfb8aa3b, v105
	v_mul_f32_e32 v106, 0xbfb8aa3b, v106
	v_mul_f32_e32 v107, 0xbfb8aa3b, v107
	v_exp_f32_e32 v104, v104
	v_exp_f32_e32 v105, v105
	v_exp_f32_e32 v106, v106
	v_exp_f32_e32 v107, v107
	v_add_f32_e32 v104, 1.0, v104
	v_add_f32_e32 v105, 1.0, v105
	v_add_f32_e32 v106, 1.0, v106
	v_add_f32_e32 v107, 1.0, v107
	v_rcp_f32_e32 v220, v104
	v_rcp_f32_e32 v221, v105
	v_rcp_f32_e32 v222, v106
	v_rcp_f32_e32 v223, v107
	v_fma_f32 v224, -v104, v220, 1.0
	v_fma_f32 v225, -v105, v221, 1.0
	v_fma_f32 v226, -v106, v222, 1.0
	v_fma_f32 v227, -v107, v223, 1.0
	v_fma_f32 v104, v224, v220, v220
	v_fma_f32 v105, v225, v221, v221
	v_fma_f32 v106, v226, v222, v222
	v_fma_f32 v107, v227, v223, v223
	v_lshlrev_b32_e32 v230, 16, v172
	v_and_b32_e32 v172, 0xffff0000, v172
	v_lshlrev_b32_e32 v231, 16, v173
	v_and_b32_e32 v173, 0xffff0000, v173
	v_lshlrev_b32_e32 v232, 16, v174
	v_and_b32_e32 v174, 0xffff0000, v174
	v_lshlrev_b32_e32 v233, 16, v175
	v_and_b32_e32 v175, 0xffff0000, v175
	v_fma_f32 v104, v104, v232, v230
	v_fma_f32 v105, v105, v174, v172
	v_fma_f32 v106, v106, v233, v231
	v_fma_f32 v107, v107, v175, v173
	global_store_dwordx4 v252, v[104:107], s[42:43] offset:64
	v_mul_f32_e32 v100, v100, v209
	v_mul_f32_e32 v101, v101, v209
	v_mul_f32_e32 v102, v102, v209
	v_mul_f32_e32 v103, v103, v209
	v_mul_f32_e32 v100, 0xbfb8aa3b, v100
	v_mul_f32_e32 v101, 0xbfb8aa3b, v101
	v_mul_f32_e32 v102, 0xbfb8aa3b, v102
	v_mul_f32_e32 v103, 0xbfb8aa3b, v103
	v_exp_f32_e32 v100, v100
	v_exp_f32_e32 v101, v101
	v_exp_f32_e32 v102, v102
	v_exp_f32_e32 v103, v103
	v_add_f32_e32 v100, 1.0, v100
	v_add_f32_e32 v101, 1.0, v101
	v_add_f32_e32 v102, 1.0, v102
	v_add_f32_e32 v103, 1.0, v103
	v_rcp_f32_e32 v220, v100
	v_rcp_f32_e32 v221, v101
	v_rcp_f32_e32 v222, v102
	v_rcp_f32_e32 v223, v103
	v_fma_f32 v224, -v100, v220, 1.0
	v_fma_f32 v225, -v101, v221, 1.0
	v_fma_f32 v226, -v102, v222, 1.0
	v_fma_f32 v227, -v103, v223, 1.0
	v_fma_f32 v100, v224, v220, v220
	v_fma_f32 v101, v225, v221, v221
	v_fma_f32 v102, v226, v222, v222
	v_fma_f32 v103, v227, v223, v223
	v_lshlrev_b32_e32 v230, 16, v240
	v_and_b32_e32 v240, 0xffff0000, v240
	v_lshlrev_b32_e32 v231, 16, v241
	v_and_b32_e32 v241, 0xffff0000, v241
	v_lshlrev_b32_e32 v232, 16, v242
	v_and_b32_e32 v242, 0xffff0000, v242
	v_lshlrev_b32_e32 v233, 16, v243
	v_and_b32_e32 v243, 0xffff0000, v243
	v_fma_f32 v100, v100, v232, v230
	v_fma_f32 v101, v101, v242, v240
	v_fma_f32 v102, v102, v233, v231
	v_fma_f32 v103, v103, v243, v241
	global_store_dwordx4 v252, v[100:103], s[42:43] offset:512
	v_mul_f32_e32 v96, v96, v209
	v_mul_f32_e32 v97, v97, v209
	v_mul_f32_e32 v98, v98, v209
	v_mul_f32_e32 v99, v99, v209
	v_mul_f32_e32 v96, 0xbfb8aa3b, v96
	v_mul_f32_e32 v97, 0xbfb8aa3b, v97
	v_mul_f32_e32 v98, 0xbfb8aa3b, v98
	v_mul_f32_e32 v99, 0xbfb8aa3b, v99
	v_exp_f32_e32 v96, v96
	v_exp_f32_e32 v97, v97
	v_exp_f32_e32 v98, v98
	v_exp_f32_e32 v99, v99
	v_add_f32_e32 v96, 1.0, v96
	v_add_f32_e32 v97, 1.0, v97
	v_add_f32_e32 v98, 1.0, v98
	v_add_f32_e32 v99, 1.0, v99
	v_rcp_f32_e32 v220, v96
	v_rcp_f32_e32 v221, v97
	v_rcp_f32_e32 v222, v98
	v_rcp_f32_e32 v223, v99
	v_fma_f32 v224, -v96, v220, 1.0
	v_fma_f32 v225, -v97, v221, 1.0
	v_fma_f32 v226, -v98, v222, 1.0
	v_fma_f32 v227, -v99, v223, 1.0
	v_fma_f32 v96, v224, v220, v220
	v_fma_f32 v97, v225, v221, v221
	v_fma_f32 v98, v226, v222, v222
	v_fma_f32 v99, v227, v223, v223
	v_lshlrev_b32_e32 v230, 16, v244
	v_and_b32_e32 v244, 0xffff0000, v244
	v_lshlrev_b32_e32 v231, 16, v245
	v_and_b32_e32 v245, 0xffff0000, v245
	v_lshlrev_b32_e32 v232, 16, v246
	v_and_b32_e32 v246, 0xffff0000, v246
	v_lshlrev_b32_e32 v233, 16, v247
	v_and_b32_e32 v247, 0xffff0000, v247
	v_fma_f32 v96, v96, v232, v230
	v_fma_f32 v97, v97, v246, v244
	v_fma_f32 v98, v98, v233, v231
	v_fma_f32 v99, v99, v247, v245
	global_store_dwordx4 v252, v[96:99], s[42:43] offset:576
	v_add_u32_e32 v196, 0x4000, v146
	global_load_dwordx4 v[96:99], v196, s[16:17]
	global_load_dwordx4 v[100:103], v196, s[16:17] offset:16
	v_add_u32_e32 v148, 0x4800, v146
	global_load_dwordx4 v[104:107], v148, s[16:17]
	global_load_dwordx4 v[108:111], v148, s[16:17] offset:16
	v_add_u32_e32 v188, 0x5000, v146
	global_load_dwordx4 v[112:115], v188, s[16:17]
	global_load_dwordx4 v[116:119], v188, s[16:17] offset:16
	v_add_u32_e32 v192, 0x5800, v146
	global_load_dwordx4 v[120:123], v192, s[16:17]
	global_load_dwordx4 v[124:127], v192, s[16:17] offset:16
	v_add_u32_e32 v196, 0x80000, v140
	global_load_dwordx2 v[152:153], v196, s[58:59] offset:0
	global_load_dwordx2 v[154:155], v196, s[56:57] offset:0
	global_load_dwordx2 v[156:157], v196, s[58:59] offset:32
	global_load_dwordx2 v[158:159], v196, s[56:57] offset:32
	global_load_dwordx2 v[160:161], v196, s[58:59] offset:256
	global_load_dwordx2 v[162:163], v196, s[56:57] offset:256
	global_load_dwordx2 v[164:165], v196, s[58:59] offset:288
	global_load_dwordx2 v[166:167], v196, s[56:57] offset:288
	v_add_u32_e32 v148, 0x90000, v140
	global_load_dwordx2 v[168:169], v148, s[58:59] offset:0
	global_load_dwordx2 v[170:171], v148, s[56:57] offset:0
	global_load_dwordx2 v[172:173], v148, s[58:59] offset:32
	global_load_dwordx2 v[174:175], v148, s[56:57] offset:32
	global_load_dwordx2 v[240:241], v148, s[58:59] offset:256
	global_load_dwordx2 v[242:243], v148, s[56:57] offset:256
	global_load_dwordx2 v[244:245], v148, s[58:59] offset:288
	global_load_dwordx2 v[246:247], v148, s[56:57] offset:288
	s_waitcnt vmcnt(32)
	v_add_u32_e32 v188, 0x20000, v140
	v_mul_f32_e32 v92, v92, v210
	v_mul_f32_e32 v93, v93, v210
	v_mul_f32_e32 v94, v94, v210
	v_mul_f32_e32 v95, v95, v210
	v_mul_f32_e32 v92, 0xbfb8aa3b, v92
	v_mul_f32_e32 v93, 0xbfb8aa3b, v93
	v_mul_f32_e32 v94, 0xbfb8aa3b, v94
	v_mul_f32_e32 v95, 0xbfb8aa3b, v95
	v_exp_f32_e32 v92, v92
	v_exp_f32_e32 v93, v93
	v_exp_f32_e32 v94, v94
	v_exp_f32_e32 v95, v95
	v_add_f32_e32 v92, 1.0, v92
	v_add_f32_e32 v93, 1.0, v93
	v_add_f32_e32 v94, 1.0, v94
	v_add_f32_e32 v95, 1.0, v95
	v_rcp_f32_e32 v220, v92
	v_rcp_f32_e32 v221, v93
	v_rcp_f32_e32 v222, v94
	v_rcp_f32_e32 v223, v95
	v_fma_f32 v224, -v92, v220, 1.0
	v_fma_f32 v225, -v93, v221, 1.0
	v_fma_f32 v226, -v94, v222, 1.0
	v_fma_f32 v227, -v95, v223, 1.0
	v_fma_f32 v92, v224, v220, v220
	v_fma_f32 v93, v225, v221, v221
	v_fma_f32 v94, v226, v222, v222
	v_fma_f32 v95, v227, v223, v223
	v_lshlrev_b32_e32 v230, 16, v182
	v_and_b32_e32 v182, 0xffff0000, v182
	v_lshlrev_b32_e32 v231, 16, v183
	v_and_b32_e32 v183, 0xffff0000, v183
	v_lshlrev_b32_e32 v232, 16, v184
	v_and_b32_e32 v184, 0xffff0000, v184
	v_lshlrev_b32_e32 v233, 16, v185
	v_and_b32_e32 v185, 0xffff0000, v185
	v_fma_f32 v92, v92, v232, v230
	v_fma_f32 v93, v93, v184, v182
	v_fma_f32 v94, v94, v233, v231
	v_fma_f32 v95, v95, v185, v183
	v_lshlrev_b32_e32 v252, 1, v188
	global_store_dwordx4 v252, v[92:95], s[42:43] offset:0
	v_mul_f32_e32 v88, v88, v210
	v_mul_f32_e32 v89, v89, v210
	v_mul_f32_e32 v90, v90, v210
	v_mul_f32_e32 v91, v91, v210
	v_mul_f32_e32 v88, 0xbfb8aa3b, v88
	v_mul_f32_e32 v89, 0xbfb8aa3b, v89
	v_mul_f32_e32 v90, 0xbfb8aa3b, v90
	v_mul_f32_e32 v91, 0xbfb8aa3b, v91
	v_exp_f32_e32 v88, v88
	v_exp_f32_e32 v89, v89
	v_exp_f32_e32 v90, v90
	v_exp_f32_e32 v91, v91
	v_add_f32_e32 v88, 1.0, v88
	v_add_f32_e32 v89, 1.0, v89
	v_add_f32_e32 v90, 1.0, v90
	v_add_f32_e32 v91, 1.0, v91
	v_rcp_f32_e32 v220, v88
	v_rcp_f32_e32 v221, v89
	v_rcp_f32_e32 v222, v90
	v_rcp_f32_e32 v223, v91
	v_fma_f32 v224, -v88, v220, 1.0
	v_fma_f32 v225, -v89, v221, 1.0
	v_fma_f32 v226, -v90, v222, 1.0
	v_fma_f32 v227, -v91, v223, 1.0
	v_fma_f32 v88, v224, v220, v220
	v_fma_f32 v89, v225, v221, v221
	v_fma_f32 v90, v226, v222, v222
	v_fma_f32 v91, v227, v223, v223
	v_lshlrev_b32_e32 v230, 16, v186
	v_and_b32_e32 v186, 0xffff0000, v186
	v_lshlrev_b32_e32 v231, 16, v187
	v_and_b32_e32 v187, 0xffff0000, v187
	v_lshlrev_b32_e32 v232, 16, v200
	v_and_b32_e32 v200, 0xffff0000, v200
	v_lshlrev_b32_e32 v233, 16, v201
	v_and_b32_e32 v201, 0xffff0000, v201
	v_fma_f32 v88, v88, v232, v230
	v_fma_f32 v89, v89, v200, v186
	v_fma_f32 v90, v90, v233, v231
	v_fma_f32 v91, v91, v201, v187
	global_store_dwordx4 v252, v[88:91], s[42:43] offset:64
	v_mul_f32_e32 v84, v84, v210
	v_mul_f32_e32 v85, v85, v210
	v_mul_f32_e32 v86, v86, v210
	v_mul_f32_e32 v87, v87, v210
	v_mul_f32_e32 v84, 0xbfb8aa3b, v84
	v_mul_f32_e32 v85, 0xbfb8aa3b, v85
	v_mul_f32_e32 v86, 0xbfb8aa3b, v86
	v_mul_f32_e32 v87, 0xbfb8aa3b, v87
	v_exp_f32_e32 v84, v84
	v_exp_f32_e32 v85, v85
	v_exp_f32_e32 v86, v86
	v_exp_f32_e32 v87, v87
	v_add_f32_e32 v84, 1.0, v84
	v_add_f32_e32 v85, 1.0, v85
	v_add_f32_e32 v86, 1.0, v86
	v_add_f32_e32 v87, 1.0, v87
	v_rcp_f32_e32 v220, v84
	v_rcp_f32_e32 v221, v85
	v_rcp_f32_e32 v222, v86
	v_rcp_f32_e32 v223, v87
	v_fma_f32 v224, -v84, v220, 1.0
	v_fma_f32 v225, -v85, v221, 1.0
	v_fma_f32 v226, -v86, v222, 1.0
	v_fma_f32 v227, -v87, v223, 1.0
	v_fma_f32 v84, v224, v220, v220
	v_fma_f32 v85, v225, v221, v221
	v_fma_f32 v86, v226, v222, v222
	v_fma_f32 v87, v227, v223, v223
	v_lshlrev_b32_e32 v230, 16, v202
	v_and_b32_e32 v202, 0xffff0000, v202
	v_lshlrev_b32_e32 v231, 16, v203
	v_and_b32_e32 v203, 0xffff0000, v203
	v_lshlrev_b32_e32 v232, 16, v204
	v_and_b32_e32 v204, 0xffff0000, v204
	v_lshlrev_b32_e32 v233, 16, v205
	v_and_b32_e32 v205, 0xffff0000, v205
	v_fma_f32 v84, v84, v232, v230
	v_fma_f32 v85, v85, v204, v202
	v_fma_f32 v86, v86, v233, v231
	v_fma_f32 v87, v87, v205, v203
	global_store_dwordx4 v252, v[84:87], s[42:43] offset:512
	v_mul_f32_e32 v80, v80, v210
	v_mul_f32_e32 v81, v81, v210
	v_mul_f32_e32 v82, v82, v210
	v_mul_f32_e32 v83, v83, v210
	v_mul_f32_e32 v80, 0xbfb8aa3b, v80
	v_mul_f32_e32 v81, 0xbfb8aa3b, v81
	v_mul_f32_e32 v82, 0xbfb8aa3b, v82
	v_mul_f32_e32 v83, 0xbfb8aa3b, v83
	v_exp_f32_e32 v80, v80
	v_exp_f32_e32 v81, v81
	v_exp_f32_e32 v82, v82
	v_exp_f32_e32 v83, v83
	v_add_f32_e32 v80, 1.0, v80
	v_add_f32_e32 v81, 1.0, v81
	v_add_f32_e32 v82, 1.0, v82
	v_add_f32_e32 v83, 1.0, v83
	v_rcp_f32_e32 v220, v80
	v_rcp_f32_e32 v221, v81
	v_rcp_f32_e32 v222, v82
	v_rcp_f32_e32 v223, v83
	v_fma_f32 v224, -v80, v220, 1.0
	v_fma_f32 v225, -v81, v221, 1.0
	v_fma_f32 v226, -v82, v222, 1.0
	v_fma_f32 v227, -v83, v223, 1.0
	v_fma_f32 v80, v224, v220, v220
	v_fma_f32 v81, v225, v221, v221
	v_fma_f32 v82, v226, v222, v222
	v_fma_f32 v83, v227, v223, v223
	v_lshlrev_b32_e32 v230, 16, v134
	v_and_b32_e32 v134, 0xffff0000, v134
	v_lshlrev_b32_e32 v231, 16, v135
	v_and_b32_e32 v135, 0xffff0000, v135
	v_lshlrev_b32_e32 v232, 16, v136
	v_and_b32_e32 v136, 0xffff0000, v136
	v_lshlrev_b32_e32 v233, 16, v137
	v_and_b32_e32 v137, 0xffff0000, v137
	v_fma_f32 v80, v80, v232, v230
	v_fma_f32 v81, v81, v136, v134
	v_fma_f32 v82, v82, v233, v231
	v_fma_f32 v83, v83, v137, v135
	global_store_dwordx4 v252, v[80:83], s[42:43] offset:576
	v_add_u32_e32 v192, 0x30000, v140
	v_mul_f32_e32 v76, v76, v211
	v_mul_f32_e32 v77, v77, v211
	v_mul_f32_e32 v78, v78, v211
	v_mul_f32_e32 v79, v79, v211
	v_mul_f32_e32 v76, 0xbfb8aa3b, v76
	v_mul_f32_e32 v77, 0xbfb8aa3b, v77
	v_mul_f32_e32 v78, 0xbfb8aa3b, v78
	v_mul_f32_e32 v79, 0xbfb8aa3b, v79
	v_exp_f32_e32 v76, v76
	v_exp_f32_e32 v77, v77
	v_exp_f32_e32 v78, v78
	v_exp_f32_e32 v79, v79
	v_add_f32_e32 v76, 1.0, v76
	v_add_f32_e32 v77, 1.0, v77
	v_add_f32_e32 v78, 1.0, v78
	v_add_f32_e32 v79, 1.0, v79
	v_rcp_f32_e32 v220, v76
	v_rcp_f32_e32 v221, v77
	v_rcp_f32_e32 v222, v78
	v_rcp_f32_e32 v223, v79
	v_fma_f32 v224, -v76, v220, 1.0
	v_fma_f32 v225, -v77, v221, 1.0
	v_fma_f32 v226, -v78, v222, 1.0
	v_fma_f32 v227, -v79, v223, 1.0
	v_fma_f32 v76, v224, v220, v220
	v_fma_f32 v77, v225, v221, v221
	v_fma_f32 v78, v226, v222, v222
	v_fma_f32 v79, v227, v223, v223
	v_lshlrev_b32_e32 v230, 16, v138
	v_and_b32_e32 v138, 0xffff0000, v138
	v_lshlrev_b32_e32 v231, 16, v139
	v_and_b32_e32 v139, 0xffff0000, v139
	v_lshlrev_b32_e32 v232, 16, v142
	v_and_b32_e32 v142, 0xffff0000, v142
	v_lshlrev_b32_e32 v233, 16, v143
	v_and_b32_e32 v143, 0xffff0000, v143
	v_fma_f32 v76, v76, v232, v230
	v_fma_f32 v77, v77, v142, v138
	v_fma_f32 v78, v78, v233, v231
	v_fma_f32 v79, v79, v143, v139
	v_lshlrev_b32_e32 v252, 1, v192
	global_store_dwordx4 v252, v[76:79], s[42:43] offset:0
	v_mul_f32_e32 v72, v72, v211
	v_mul_f32_e32 v73, v73, v211
	v_mul_f32_e32 v74, v74, v211
	v_mul_f32_e32 v75, v75, v211
	v_mul_f32_e32 v72, 0xbfb8aa3b, v72
	v_mul_f32_e32 v73, 0xbfb8aa3b, v73
	v_mul_f32_e32 v74, 0xbfb8aa3b, v74
	v_mul_f32_e32 v75, 0xbfb8aa3b, v75
	v_exp_f32_e32 v72, v72
	v_exp_f32_e32 v73, v73
	v_exp_f32_e32 v74, v74
	v_exp_f32_e32 v75, v75
	v_add_f32_e32 v72, 1.0, v72
	v_add_f32_e32 v73, 1.0, v73
	v_add_f32_e32 v74, 1.0, v74
	v_add_f32_e32 v75, 1.0, v75
	v_rcp_f32_e32 v220, v72
	v_rcp_f32_e32 v221, v73
	v_rcp_f32_e32 v222, v74
	v_rcp_f32_e32 v223, v75
	v_fma_f32 v224, -v72, v220, 1.0
	v_fma_f32 v225, -v73, v221, 1.0
	v_fma_f32 v226, -v74, v222, 1.0
	v_fma_f32 v227, -v75, v223, 1.0
	v_fma_f32 v72, v224, v220, v220
	v_fma_f32 v73, v225, v221, v221
	v_fma_f32 v74, v226, v222, v222
	v_fma_f32 v75, v227, v223, v223
	v_lshlrev_b32_e32 v230, 16, v144
	v_and_b32_e32 v144, 0xffff0000, v144
	v_lshlrev_b32_e32 v231, 16, v145
	v_and_b32_e32 v145, 0xffff0000, v145
	v_lshlrev_b32_e32 v232, 16, v190
	v_and_b32_e32 v190, 0xffff0000, v190
	v_lshlrev_b32_e32 v233, 16, v191
	v_and_b32_e32 v191, 0xffff0000, v191
	v_fma_f32 v72, v72, v232, v230
	v_fma_f32 v73, v73, v190, v144
	v_fma_f32 v74, v74, v233, v231
	v_fma_f32 v75, v75, v191, v145
	global_store_dwordx4 v252, v[72:75], s[42:43] offset:64
	v_mul_f32_e32 v68, v68, v211
	v_mul_f32_e32 v69, v69, v211
	v_mul_f32_e32 v70, v70, v211
	v_mul_f32_e32 v71, v71, v211
	v_mul_f32_e32 v68, 0xbfb8aa3b, v68
	v_mul_f32_e32 v69, 0xbfb8aa3b, v69
	v_mul_f32_e32 v70, 0xbfb8aa3b, v70
	v_mul_f32_e32 v71, 0xbfb8aa3b, v71
	v_exp_f32_e32 v68, v68
	v_exp_f32_e32 v69, v69
	v_exp_f32_e32 v70, v70
	v_exp_f32_e32 v71, v71
	v_add_f32_e32 v68, 1.0, v68
	v_add_f32_e32 v69, 1.0, v69
	v_add_f32_e32 v70, 1.0, v70
	v_add_f32_e32 v71, 1.0, v71
	v_rcp_f32_e32 v220, v68
	v_rcp_f32_e32 v221, v69
	v_rcp_f32_e32 v222, v70
	v_rcp_f32_e32 v223, v71
	v_fma_f32 v224, -v68, v220, 1.0
	v_fma_f32 v225, -v69, v221, 1.0
	v_fma_f32 v226, -v70, v222, 1.0
	v_fma_f32 v227, -v71, v223, 1.0
	v_fma_f32 v68, v224, v220, v220
	v_fma_f32 v69, v225, v221, v221
	v_fma_f32 v70, v226, v222, v222
	v_fma_f32 v71, v227, v223, v223
	v_lshlrev_b32_e32 v230, 16, v194
	v_and_b32_e32 v194, 0xffff0000, v194
	v_lshlrev_b32_e32 v231, 16, v195
	v_and_b32_e32 v195, 0xffff0000, v195
	v_lshlrev_b32_e32 v232, 16, v248
	v_and_b32_e32 v248, 0xffff0000, v248
	v_lshlrev_b32_e32 v233, 16, v249
	v_and_b32_e32 v249, 0xffff0000, v249
	v_fma_f32 v68, v68, v232, v230
	v_fma_f32 v69, v69, v248, v194
	v_fma_f32 v70, v70, v233, v231
	v_fma_f32 v71, v71, v249, v195
	global_store_dwordx4 v252, v[68:71], s[42:43] offset:512
	v_mul_f32_e32 v64, v64, v211
	v_mul_f32_e32 v65, v65, v211
	v_mul_f32_e32 v66, v66, v211
	v_mul_f32_e32 v67, v67, v211
	v_mul_f32_e32 v64, 0xbfb8aa3b, v64
	v_mul_f32_e32 v65, 0xbfb8aa3b, v65
	v_mul_f32_e32 v66, 0xbfb8aa3b, v66
	v_mul_f32_e32 v67, 0xbfb8aa3b, v67
	v_exp_f32_e32 v64, v64
	v_exp_f32_e32 v65, v65
	v_exp_f32_e32 v66, v66
	v_exp_f32_e32 v67, v67
	v_add_f32_e32 v64, 1.0, v64
	v_add_f32_e32 v65, 1.0, v65
	v_add_f32_e32 v66, 1.0, v66
	v_add_f32_e32 v67, 1.0, v67
	v_rcp_f32_e32 v220, v64
	v_rcp_f32_e32 v221, v65
	v_rcp_f32_e32 v222, v66
	v_rcp_f32_e32 v223, v67
	v_fma_f32 v224, -v64, v220, 1.0
	v_fma_f32 v225, -v65, v221, 1.0
	v_fma_f32 v226, -v66, v222, 1.0
	v_fma_f32 v227, -v67, v223, 1.0
	v_fma_f32 v64, v224, v220, v220
	v_fma_f32 v65, v225, v221, v221
	v_fma_f32 v66, v226, v222, v222
	v_fma_f32 v67, v227, v223, v223
	v_lshlrev_b32_e32 v230, 16, v150
	v_and_b32_e32 v150, 0xffff0000, v150
	v_lshlrev_b32_e32 v231, 16, v151
	v_and_b32_e32 v151, 0xffff0000, v151
	v_lshlrev_b32_e32 v232, 16, v238
	v_and_b32_e32 v238, 0xffff0000, v238
	v_lshlrev_b32_e32 v233, 16, v239
	v_and_b32_e32 v239, 0xffff0000, v239
	v_fma_f32 v64, v64, v232, v230
	v_fma_f32 v65, v65, v238, v150
	v_fma_f32 v66, v66, v233, v231
	v_fma_f32 v67, v67, v239, v151
	global_store_dwordx4 v252, v[64:67], s[42:43] offset:576
	v_add_u32_e32 v196, 0xa0000, v140
	global_load_dwordx2 v[182:183], v196, s[58:59] offset:0
	global_load_dwordx2 v[184:185], v196, s[56:57] offset:0
	global_load_dwordx2 v[186:187], v196, s[58:59] offset:32
	global_load_dwordx2 v[200:201], v196, s[56:57] offset:32
	global_load_dwordx2 v[202:203], v196, s[58:59] offset:256
	global_load_dwordx2 v[204:205], v196, s[56:57] offset:256
	global_load_dwordx2 v[134:135], v196, s[58:59] offset:288
	global_load_dwordx2 v[136:137], v196, s[56:57] offset:288
	v_add_u32_e32 v148, 0xb0000, v140
	global_load_dwordx2 v[138:139], v148, s[58:59] offset:0
	global_load_dwordx2 v[142:143], v148, s[56:57] offset:0
	global_load_dwordx2 v[144:145], v148, s[58:59] offset:32
	global_load_dwordx2 v[190:191], v148, s[56:57] offset:32
	global_load_dwordx2 v[194:195], v148, s[58:59] offset:256
	global_load_dwordx2 v[248:249], v148, s[56:57] offset:256
	global_load_dwordx2 v[150:151], v148, s[58:59] offset:288
	v_add_u32_e32 v188, 0xb0000, v140
	global_load_dwordx2 v[234:235], v188, s[56:57] offset:288
	s_waitcnt vmcnt(40)
	v_add_f32_e32 v96, v96, v97
	v_add_f32_e32 v98, v98, v99
	v_add_f32_e32 v100, v100, v101
	v_add_f32_e32 v102, v102, v103
	v_add_f32_e32 v96, v96, v98
	v_add_f32_e32 v100, v100, v102
	v_add_f32_e32 v96, v96, v100
	v_add_f32_e32 v104, v104, v105
	v_add_f32_e32 v106, v106, v107
	v_add_f32_e32 v108, v108, v109
	v_add_f32_e32 v110, v110, v111
	v_add_f32_e32 v104, v104, v106
	v_add_f32_e32 v108, v108, v110
	v_add_f32_e32 v104, v104, v108
	v_add_f32_e32 v112, v112, v113
	v_add_f32_e32 v114, v114, v115
	v_add_f32_e32 v116, v116, v117
	v_add_f32_e32 v118, v118, v119
	v_add_f32_e32 v112, v112, v114
	v_add_f32_e32 v116, v116, v118
	v_add_f32_e32 v112, v112, v116
	v_add_f32_e32 v120, v120, v121
	v_add_f32_e32 v122, v122, v123
	v_add_f32_e32 v124, v124, v125
	v_add_f32_e32 v126, v126, v127
	v_add_f32_e32 v120, v120, v122
	v_add_f32_e32 v124, v124, v126
	v_add_f32_e32 v120, v120, v124
	ds_bpermute_b32 v97, v207, v96
	ds_bpermute_b32 v105, v207, v104
	ds_bpermute_b32 v113, v207, v112
	ds_bpermute_b32 v121, v207, v120
	s_waitcnt lgkmcnt(0)
	v_add_f32_e32 v96, v96, v97
	v_add_f32_e32 v104, v104, v105
	v_add_f32_e32 v112, v112, v113
	v_add_f32_e32 v120, v120, v121
	ds_bpermute_b32 v97, v206, v96
	ds_bpermute_b32 v105, v206, v104
	ds_bpermute_b32 v113, v206, v112
	ds_bpermute_b32 v121, v206, v120
	s_waitcnt lgkmcnt(0)
	v_add_f32_e32 v96, v96, v97
	v_add_f32_e32 v104, v104, v105
	v_add_f32_e32 v112, v112, v113
	v_add_f32_e32 v120, v120, v121
	v_mul_f32_e32 v96, 0x3a000000, v96
	v_add_f32_e32 v96, 0x358637bd, v96
	v_mul_f32_e32 v104, 0x3a000000, v104
	v_add_f32_e32 v104, 0x358637bd, v104
	v_mul_f32_e32 v112, 0x3a000000, v112
	v_add_f32_e32 v112, 0x358637bd, v112
	v_mul_f32_e32 v120, 0x3a000000, v120
	v_add_f32_e32 v120, 0x358637bd, v120
	v_rsq_f32_e32 v96, v96
	v_rsq_f32_e32 v104, v104
	v_rsq_f32_e32 v112, v112
	v_rsq_f32_e32 v120, v120
	s_nop 0
	v_mov_b32_e32 v212, v96
	v_mov_b32_e32 v213, v104
	v_mov_b32_e32 v214, v112
	v_mov_b32_e32 v215, v120
	s_waitcnt vmcnt(24)
	v_add_u32_e32 v192, 0x80000, v140
	v_mul_f32_e32 v60, v60, v212
	v_mul_f32_e32 v61, v61, v212
	v_mul_f32_e32 v62, v62, v212
	v_mul_f32_e32 v63, v63, v212
	v_mul_f32_e32 v60, 0xbfb8aa3b, v60
	v_mul_f32_e32 v61, 0xbfb8aa3b, v61
	v_mul_f32_e32 v62, 0xbfb8aa3b, v62
	v_mul_f32_e32 v63, 0xbfb8aa3b, v63
	v_exp_f32_e32 v60, v60
	v_exp_f32_e32 v61, v61
	v_exp_f32_e32 v62, v62
	v_exp_f32_e32 v63, v63
	v_add_f32_e32 v60, 1.0, v60
	v_add_f32_e32 v61, 1.0, v61
	v_add_f32_e32 v62, 1.0, v62
	v_add_f32_e32 v63, 1.0, v63
	v_rcp_f32_e32 v220, v60
	v_rcp_f32_e32 v221, v61
	v_rcp_f32_e32 v222, v62
	v_rcp_f32_e32 v223, v63
	v_fma_f32 v224, -v60, v220, 1.0
	v_fma_f32 v225, -v61, v221, 1.0
	v_fma_f32 v226, -v62, v222, 1.0
	v_fma_f32 v227, -v63, v223, 1.0
	v_fma_f32 v60, v224, v220, v220
	v_fma_f32 v61, v225, v221, v221
	v_fma_f32 v62, v226, v222, v222
	v_fma_f32 v63, v227, v223, v223
	v_lshlrev_b32_e32 v230, 16, v152
	v_and_b32_e32 v152, 0xffff0000, v152
	v_lshlrev_b32_e32 v231, 16, v153
	v_and_b32_e32 v153, 0xffff0000, v153
	v_lshlrev_b32_e32 v232, 16, v154
	v_and_b32_e32 v154, 0xffff0000, v154
	v_lshlrev_b32_e32 v233, 16, v155
	v_and_b32_e32 v155, 0xffff0000, v155
	v_fma_f32 v60, v60, v232, v230
	v_fma_f32 v61, v61, v154, v152
	v_fma_f32 v62, v62, v233, v231
	v_fma_f32 v63, v63, v155, v153
	v_lshlrev_b32_e32 v252, 1, v192
	global_store_dwordx4 v252, v[60:63], s[42:43] offset:0
	v_mul_f32_e32 v56, v56, v212
	v_mul_f32_e32 v57, v57, v212
	v_mul_f32_e32 v58, v58, v212
	v_mul_f32_e32 v59, v59, v212
	v_mul_f32_e32 v56, 0xbfb8aa3b, v56
	v_mul_f32_e32 v57, 0xbfb8aa3b, v57
	v_mul_f32_e32 v58, 0xbfb8aa3b, v58
	v_mul_f32_e32 v59, 0xbfb8aa3b, v59
	v_exp_f32_e32 v56, v56
	v_exp_f32_e32 v57, v57
	v_exp_f32_e32 v58, v58
	v_exp_f32_e32 v59, v59
	v_add_f32_e32 v56, 1.0, v56
	v_add_f32_e32 v57, 1.0, v57
	v_add_f32_e32 v58, 1.0, v58
	v_add_f32_e32 v59, 1.0, v59
	v_rcp_f32_e32 v220, v56
	v_rcp_f32_e32 v221, v57
	v_rcp_f32_e32 v222, v58
	v_rcp_f32_e32 v223, v59
	v_fma_f32 v224, -v56, v220, 1.0
	v_fma_f32 v225, -v57, v221, 1.0
	v_fma_f32 v226, -v58, v222, 1.0
	v_fma_f32 v227, -v59, v223, 1.0
	v_fma_f32 v56, v224, v220, v220
	v_fma_f32 v57, v225, v221, v221
	v_fma_f32 v58, v226, v222, v222
	v_fma_f32 v59, v227, v223, v223
	v_lshlrev_b32_e32 v230, 16, v156
	v_and_b32_e32 v156, 0xffff0000, v156
	v_lshlrev_b32_e32 v231, 16, v157
	v_and_b32_e32 v157, 0xffff0000, v157
	v_lshlrev_b32_e32 v232, 16, v158
	v_and_b32_e32 v158, 0xffff0000, v158
	v_lshlrev_b32_e32 v233, 16, v159
	v_and_b32_e32 v159, 0xffff0000, v159
	v_fma_f32 v56, v56, v232, v230
	v_fma_f32 v57, v57, v158, v156
	v_fma_f32 v58, v58, v233, v231
	v_fma_f32 v59, v59, v159, v157
	global_store_dwordx4 v252, v[56:59], s[42:43] offset:64
	v_mul_f32_e32 v52, v52, v212
	v_mul_f32_e32 v53, v53, v212
	v_mul_f32_e32 v54, v54, v212
	v_mul_f32_e32 v55, v55, v212
	v_mul_f32_e32 v52, 0xbfb8aa3b, v52
	v_mul_f32_e32 v53, 0xbfb8aa3b, v53
	v_mul_f32_e32 v54, 0xbfb8aa3b, v54
	v_mul_f32_e32 v55, 0xbfb8aa3b, v55
	v_exp_f32_e32 v52, v52
	v_exp_f32_e32 v53, v53
	v_exp_f32_e32 v54, v54
	v_exp_f32_e32 v55, v55
	v_add_f32_e32 v52, 1.0, v52
	v_add_f32_e32 v53, 1.0, v53
	v_add_f32_e32 v54, 1.0, v54
	v_add_f32_e32 v55, 1.0, v55
	v_rcp_f32_e32 v220, v52
	v_rcp_f32_e32 v221, v53
	v_rcp_f32_e32 v222, v54
	v_rcp_f32_e32 v223, v55
	v_fma_f32 v224, -v52, v220, 1.0
	v_fma_f32 v225, -v53, v221, 1.0
	v_fma_f32 v226, -v54, v222, 1.0
	v_fma_f32 v227, -v55, v223, 1.0
	v_fma_f32 v52, v224, v220, v220
	v_fma_f32 v53, v225, v221, v221
	v_fma_f32 v54, v226, v222, v222
	v_fma_f32 v55, v227, v223, v223
	v_lshlrev_b32_e32 v230, 16, v160
	v_and_b32_e32 v160, 0xffff0000, v160
	v_lshlrev_b32_e32 v231, 16, v161
	v_and_b32_e32 v161, 0xffff0000, v161
	v_lshlrev_b32_e32 v232, 16, v162
	v_and_b32_e32 v162, 0xffff0000, v162
	v_lshlrev_b32_e32 v233, 16, v163
	v_and_b32_e32 v163, 0xffff0000, v163
	v_fma_f32 v52, v52, v232, v230
	v_fma_f32 v53, v53, v162, v160
	v_fma_f32 v54, v54, v233, v231
	v_fma_f32 v55, v55, v163, v161
	global_store_dwordx4 v252, v[52:55], s[42:43] offset:512
	v_mul_f32_e32 v48, v48, v212
	v_mul_f32_e32 v49, v49, v212
	v_mul_f32_e32 v50, v50, v212
	v_mul_f32_e32 v51, v51, v212
	v_mul_f32_e32 v48, 0xbfb8aa3b, v48
	v_mul_f32_e32 v49, 0xbfb8aa3b, v49
	v_mul_f32_e32 v50, 0xbfb8aa3b, v50
	v_mul_f32_e32 v51, 0xbfb8aa3b, v51
	v_exp_f32_e32 v48, v48
	v_exp_f32_e32 v49, v49
	v_exp_f32_e32 v50, v50
	v_exp_f32_e32 v51, v51
	v_add_f32_e32 v48, 1.0, v48
	v_add_f32_e32 v49, 1.0, v49
	v_add_f32_e32 v50, 1.0, v50
	v_add_f32_e32 v51, 1.0, v51
	v_rcp_f32_e32 v220, v48
	v_rcp_f32_e32 v221, v49
	v_rcp_f32_e32 v222, v50
	v_rcp_f32_e32 v223, v51
	v_fma_f32 v224, -v48, v220, 1.0
	v_fma_f32 v225, -v49, v221, 1.0
	v_fma_f32 v226, -v50, v222, 1.0
	v_fma_f32 v227, -v51, v223, 1.0
	v_fma_f32 v48, v224, v220, v220
	v_fma_f32 v49, v225, v221, v221
	v_fma_f32 v50, v226, v222, v222
	v_fma_f32 v51, v227, v223, v223
	v_lshlrev_b32_e32 v230, 16, v164
	v_and_b32_e32 v164, 0xffff0000, v164
	v_lshlrev_b32_e32 v231, 16, v165
	v_and_b32_e32 v165, 0xffff0000, v165
	v_lshlrev_b32_e32 v232, 16, v166
	v_and_b32_e32 v166, 0xffff0000, v166
	v_lshlrev_b32_e32 v233, 16, v167
	v_and_b32_e32 v167, 0xffff0000, v167
	v_fma_f32 v48, v48, v232, v230
	v_fma_f32 v49, v49, v166, v164
	v_fma_f32 v50, v50, v233, v231
	v_fma_f32 v51, v51, v167, v165
	global_store_dwordx4 v252, v[48:51], s[42:43] offset:576
	v_add_u32_e32 v196, 0x90000, v140
	v_mul_f32_e32 v44, v44, v213
	v_mul_f32_e32 v45, v45, v213
	v_mul_f32_e32 v46, v46, v213
	v_mul_f32_e32 v47, v47, v213
	v_mul_f32_e32 v44, 0xbfb8aa3b, v44
	v_mul_f32_e32 v45, 0xbfb8aa3b, v45
	v_mul_f32_e32 v46, 0xbfb8aa3b, v46
	v_mul_f32_e32 v47, 0xbfb8aa3b, v47
	v_exp_f32_e32 v44, v44
	v_exp_f32_e32 v45, v45
	v_exp_f32_e32 v46, v46
	v_exp_f32_e32 v47, v47
	v_add_f32_e32 v44, 1.0, v44
	v_add_f32_e32 v45, 1.0, v45
	v_add_f32_e32 v46, 1.0, v46
	v_add_f32_e32 v47, 1.0, v47
	v_rcp_f32_e32 v220, v44
	v_rcp_f32_e32 v221, v45
	v_rcp_f32_e32 v222, v46
	v_rcp_f32_e32 v223, v47
	v_fma_f32 v224, -v44, v220, 1.0
	v_fma_f32 v225, -v45, v221, 1.0
	v_fma_f32 v226, -v46, v222, 1.0
	v_fma_f32 v227, -v47, v223, 1.0
	v_fma_f32 v44, v224, v220, v220
	v_fma_f32 v45, v225, v221, v221
	v_fma_f32 v46, v226, v222, v222
	v_fma_f32 v47, v227, v223, v223
	v_lshlrev_b32_e32 v230, 16, v168
	v_and_b32_e32 v168, 0xffff0000, v168
	v_lshlrev_b32_e32 v231, 16, v169
	v_and_b32_e32 v169, 0xffff0000, v169
	v_lshlrev_b32_e32 v232, 16, v170
	v_and_b32_e32 v170, 0xffff0000, v170
	v_lshlrev_b32_e32 v233, 16, v171
	v_and_b32_e32 v171, 0xffff0000, v171
	v_fma_f32 v44, v44, v232, v230
	v_fma_f32 v45, v45, v170, v168
	v_fma_f32 v46, v46, v233, v231
	v_fma_f32 v47, v47, v171, v169
	v_lshlrev_b32_e32 v252, 1, v196
	global_store_dwordx4 v252, v[44:47], s[42:43] offset:0
	v_mul_f32_e32 v40, v40, v213
	v_mul_f32_e32 v41, v41, v213
	v_mul_f32_e32 v42, v42, v213
	v_mul_f32_e32 v43, v43, v213
	v_mul_f32_e32 v40, 0xbfb8aa3b, v40
	v_mul_f32_e32 v41, 0xbfb8aa3b, v41
	v_mul_f32_e32 v42, 0xbfb8aa3b, v42
	v_mul_f32_e32 v43, 0xbfb8aa3b, v43
	v_exp_f32_e32 v40, v40
	v_exp_f32_e32 v41, v41
	v_exp_f32_e32 v42, v42
	v_exp_f32_e32 v43, v43
	v_add_f32_e32 v40, 1.0, v40
	v_add_f32_e32 v41, 1.0, v41
	v_add_f32_e32 v42, 1.0, v42
	v_add_f32_e32 v43, 1.0, v43
	v_rcp_f32_e32 v220, v40
	v_rcp_f32_e32 v221, v41
	v_rcp_f32_e32 v222, v42
	v_rcp_f32_e32 v223, v43
	v_fma_f32 v224, -v40, v220, 1.0
	v_fma_f32 v225, -v41, v221, 1.0
	v_fma_f32 v226, -v42, v222, 1.0
	v_fma_f32 v227, -v43, v223, 1.0
	v_fma_f32 v40, v224, v220, v220
	v_fma_f32 v41, v225, v221, v221
	v_fma_f32 v42, v226, v222, v222
	v_fma_f32 v43, v227, v223, v223
	v_lshlrev_b32_e32 v230, 16, v172
	v_and_b32_e32 v172, 0xffff0000, v172
	v_lshlrev_b32_e32 v231, 16, v173
	v_and_b32_e32 v173, 0xffff0000, v173
	v_lshlrev_b32_e32 v232, 16, v174
	v_and_b32_e32 v174, 0xffff0000, v174
	v_lshlrev_b32_e32 v233, 16, v175
	v_and_b32_e32 v175, 0xffff0000, v175
	v_fma_f32 v40, v40, v232, v230
	v_fma_f32 v41, v41, v174, v172
	v_fma_f32 v42, v42, v233, v231
	v_fma_f32 v43, v43, v175, v173
	global_store_dwordx4 v252, v[40:43], s[42:43] offset:64
	v_mul_f32_e32 v36, v36, v213
	v_mul_f32_e32 v37, v37, v213
	v_mul_f32_e32 v38, v38, v213
	v_mul_f32_e32 v39, v39, v213
	v_mul_f32_e32 v36, 0xbfb8aa3b, v36
	v_mul_f32_e32 v37, 0xbfb8aa3b, v37
	v_mul_f32_e32 v38, 0xbfb8aa3b, v38
	v_mul_f32_e32 v39, 0xbfb8aa3b, v39
	v_exp_f32_e32 v36, v36
	v_exp_f32_e32 v37, v37
	v_exp_f32_e32 v38, v38
	v_exp_f32_e32 v39, v39
	v_add_f32_e32 v36, 1.0, v36
	v_add_f32_e32 v37, 1.0, v37
	v_add_f32_e32 v38, 1.0, v38
	v_add_f32_e32 v39, 1.0, v39
	v_rcp_f32_e32 v220, v36
	v_rcp_f32_e32 v221, v37
	v_rcp_f32_e32 v222, v38
	v_rcp_f32_e32 v223, v39
	v_fma_f32 v224, -v36, v220, 1.0
	v_fma_f32 v225, -v37, v221, 1.0
	v_fma_f32 v226, -v38, v222, 1.0
	v_fma_f32 v227, -v39, v223, 1.0
	v_fma_f32 v36, v224, v220, v220
	v_fma_f32 v37, v225, v221, v221
	v_fma_f32 v38, v226, v222, v222
	v_fma_f32 v39, v227, v223, v223
	v_lshlrev_b32_e32 v230, 16, v240
	v_and_b32_e32 v240, 0xffff0000, v240
	v_lshlrev_b32_e32 v231, 16, v241
	v_and_b32_e32 v241, 0xffff0000, v241
	v_lshlrev_b32_e32 v232, 16, v242
	v_and_b32_e32 v242, 0xffff0000, v242
	v_lshlrev_b32_e32 v233, 16, v243
	v_and_b32_e32 v243, 0xffff0000, v243
	v_fma_f32 v36, v36, v232, v230
	v_fma_f32 v37, v37, v242, v240
	v_fma_f32 v38, v38, v233, v231
	v_fma_f32 v39, v39, v243, v241
	global_store_dwordx4 v252, v[36:39], s[42:43] offset:512
	v_mul_f32_e32 v32, v32, v213
	v_mul_f32_e32 v33, v33, v213
	v_mul_f32_e32 v34, v34, v213
	v_mul_f32_e32 v35, v35, v213
	v_mul_f32_e32 v32, 0xbfb8aa3b, v32
	v_mul_f32_e32 v33, 0xbfb8aa3b, v33
	v_mul_f32_e32 v34, 0xbfb8aa3b, v34
	v_mul_f32_e32 v35, 0xbfb8aa3b, v35
	v_exp_f32_e32 v32, v32
	v_exp_f32_e32 v33, v33
	v_exp_f32_e32 v34, v34
	v_exp_f32_e32 v35, v35
	v_add_f32_e32 v32, 1.0, v32
	v_add_f32_e32 v33, 1.0, v33
	v_add_f32_e32 v34, 1.0, v34
	v_add_f32_e32 v35, 1.0, v35
	v_rcp_f32_e32 v220, v32
	v_rcp_f32_e32 v221, v33
	v_rcp_f32_e32 v222, v34
	v_rcp_f32_e32 v223, v35
	v_fma_f32 v224, -v32, v220, 1.0
	v_fma_f32 v225, -v33, v221, 1.0
	v_fma_f32 v226, -v34, v222, 1.0
	v_fma_f32 v227, -v35, v223, 1.0
	v_fma_f32 v32, v224, v220, v220
	v_fma_f32 v33, v225, v221, v221
	v_fma_f32 v34, v226, v222, v222
	v_fma_f32 v35, v227, v223, v223
	v_lshlrev_b32_e32 v230, 16, v244
	v_and_b32_e32 v244, 0xffff0000, v244
	v_lshlrev_b32_e32 v231, 16, v245
	v_and_b32_e32 v245, 0xffff0000, v245
	v_lshlrev_b32_e32 v232, 16, v246
	v_and_b32_e32 v246, 0xffff0000, v246
	v_lshlrev_b32_e32 v233, 16, v247
	v_and_b32_e32 v247, 0xffff0000, v247
	v_fma_f32 v32, v32, v232, v230
	v_fma_f32 v33, v33, v246, v244
	v_fma_f32 v34, v34, v233, v231
	v_fma_f32 v35, v35, v247, v245
	global_store_dwordx4 v252, v[32:35], s[42:43] offset:576
	s_waitcnt vmcnt(8)
	v_add_u32_e32 v148, 0xa0000, v140
	v_mul_f32_e32 v28, v28, v214
	v_mul_f32_e32 v29, v29, v214
	v_mul_f32_e32 v30, v30, v214
	v_mul_f32_e32 v31, v31, v214
	v_mul_f32_e32 v28, 0xbfb8aa3b, v28
	v_mul_f32_e32 v29, 0xbfb8aa3b, v29
	v_mul_f32_e32 v30, 0xbfb8aa3b, v30
	v_mul_f32_e32 v31, 0xbfb8aa3b, v31
	v_exp_f32_e32 v28, v28
	v_exp_f32_e32 v29, v29
	v_exp_f32_e32 v30, v30
	v_exp_f32_e32 v31, v31
	v_add_f32_e32 v28, 1.0, v28
	v_add_f32_e32 v29, 1.0, v29
	v_add_f32_e32 v30, 1.0, v30
	v_add_f32_e32 v31, 1.0, v31
	v_rcp_f32_e32 v220, v28
	v_rcp_f32_e32 v221, v29
	v_rcp_f32_e32 v222, v30
	v_rcp_f32_e32 v223, v31
	v_fma_f32 v224, -v28, v220, 1.0
	v_fma_f32 v225, -v29, v221, 1.0
	v_fma_f32 v226, -v30, v222, 1.0
	v_fma_f32 v227, -v31, v223, 1.0
	v_fma_f32 v28, v224, v220, v220
	v_fma_f32 v29, v225, v221, v221
	v_fma_f32 v30, v226, v222, v222
	v_fma_f32 v31, v227, v223, v223
	v_lshlrev_b32_e32 v230, 16, v182
	v_and_b32_e32 v182, 0xffff0000, v182
	v_lshlrev_b32_e32 v231, 16, v183
	v_and_b32_e32 v183, 0xffff0000, v183
	v_lshlrev_b32_e32 v232, 16, v184
	v_and_b32_e32 v184, 0xffff0000, v184
	v_lshlrev_b32_e32 v233, 16, v185
	v_and_b32_e32 v185, 0xffff0000, v185
	v_fma_f32 v28, v28, v232, v230
	v_fma_f32 v29, v29, v184, v182
	v_fma_f32 v30, v30, v233, v231
	v_fma_f32 v31, v31, v185, v183
	v_lshlrev_b32_e32 v252, 1, v148
	global_store_dwordx4 v252, v[28:31], s[42:43] offset:0
	v_mul_f32_e32 v24, v24, v214
	v_mul_f32_e32 v25, v25, v214
	v_mul_f32_e32 v26, v26, v214
	v_mul_f32_e32 v27, v27, v214
	v_mul_f32_e32 v24, 0xbfb8aa3b, v24
	v_mul_f32_e32 v25, 0xbfb8aa3b, v25
	v_mul_f32_e32 v26, 0xbfb8aa3b, v26
	v_mul_f32_e32 v27, 0xbfb8aa3b, v27
	v_exp_f32_e32 v24, v24
	v_exp_f32_e32 v25, v25
	v_exp_f32_e32 v26, v26
	v_exp_f32_e32 v27, v27
	v_add_f32_e32 v24, 1.0, v24
	v_add_f32_e32 v25, 1.0, v25
	v_add_f32_e32 v26, 1.0, v26
	v_add_f32_e32 v27, 1.0, v27
	v_rcp_f32_e32 v220, v24
	v_rcp_f32_e32 v221, v25
	v_rcp_f32_e32 v222, v26
	v_rcp_f32_e32 v223, v27
	v_fma_f32 v224, -v24, v220, 1.0
	v_fma_f32 v225, -v25, v221, 1.0
	v_fma_f32 v226, -v26, v222, 1.0
	v_fma_f32 v227, -v27, v223, 1.0
	v_fma_f32 v24, v224, v220, v220
	v_fma_f32 v25, v225, v221, v221
	v_fma_f32 v26, v226, v222, v222
	v_fma_f32 v27, v227, v223, v223
	v_lshlrev_b32_e32 v230, 16, v186
	v_and_b32_e32 v186, 0xffff0000, v186
	v_lshlrev_b32_e32 v231, 16, v187
	v_and_b32_e32 v187, 0xffff0000, v187
	v_lshlrev_b32_e32 v232, 16, v200
	v_and_b32_e32 v200, 0xffff0000, v200
	v_lshlrev_b32_e32 v233, 16, v201
	v_and_b32_e32 v201, 0xffff0000, v201
	v_fma_f32 v24, v24, v232, v230
	v_fma_f32 v25, v25, v200, v186
	v_fma_f32 v26, v26, v233, v231
	v_fma_f32 v27, v27, v201, v187
	global_store_dwordx4 v252, v[24:27], s[42:43] offset:64
	v_mul_f32_e32 v20, v20, v214
	v_mul_f32_e32 v21, v21, v214
	v_mul_f32_e32 v22, v22, v214
	v_mul_f32_e32 v23, v23, v214
	v_mul_f32_e32 v20, 0xbfb8aa3b, v20
	v_mul_f32_e32 v21, 0xbfb8aa3b, v21
	v_mul_f32_e32 v22, 0xbfb8aa3b, v22
	v_mul_f32_e32 v23, 0xbfb8aa3b, v23
	v_exp_f32_e32 v20, v20
	v_exp_f32_e32 v21, v21
	v_exp_f32_e32 v22, v22
	v_exp_f32_e32 v23, v23
	v_add_f32_e32 v20, 1.0, v20
	v_add_f32_e32 v21, 1.0, v21
	v_add_f32_e32 v22, 1.0, v22
	v_add_f32_e32 v23, 1.0, v23
	v_rcp_f32_e32 v220, v20
	v_rcp_f32_e32 v221, v21
	v_rcp_f32_e32 v222, v22
	v_rcp_f32_e32 v223, v23
	v_fma_f32 v224, -v20, v220, 1.0
	v_fma_f32 v225, -v21, v221, 1.0
	v_fma_f32 v226, -v22, v222, 1.0
	v_fma_f32 v227, -v23, v223, 1.0
	v_fma_f32 v20, v224, v220, v220
	v_fma_f32 v21, v225, v221, v221
	v_fma_f32 v22, v226, v222, v222
	v_fma_f32 v23, v227, v223, v223
	v_lshlrev_b32_e32 v230, 16, v202
	v_and_b32_e32 v202, 0xffff0000, v202
	v_lshlrev_b32_e32 v231, 16, v203
	v_and_b32_e32 v203, 0xffff0000, v203
	v_lshlrev_b32_e32 v232, 16, v204
	v_and_b32_e32 v204, 0xffff0000, v204
	v_lshlrev_b32_e32 v233, 16, v205
	v_and_b32_e32 v205, 0xffff0000, v205
	v_fma_f32 v20, v20, v232, v230
	v_fma_f32 v21, v21, v204, v202
	v_fma_f32 v22, v22, v233, v231
	v_fma_f32 v23, v23, v205, v203
	global_store_dwordx4 v252, v[20:23], s[42:43] offset:512
	v_mul_f32_e32 v16, v16, v214
	v_mul_f32_e32 v17, v17, v214
	v_mul_f32_e32 v18, v18, v214
	v_mul_f32_e32 v19, v19, v214
	v_mul_f32_e32 v16, 0xbfb8aa3b, v16
	v_mul_f32_e32 v17, 0xbfb8aa3b, v17
	v_mul_f32_e32 v18, 0xbfb8aa3b, v18
	v_mul_f32_e32 v19, 0xbfb8aa3b, v19
	v_exp_f32_e32 v16, v16
	v_exp_f32_e32 v17, v17
	v_exp_f32_e32 v18, v18
	v_exp_f32_e32 v19, v19
	v_add_f32_e32 v16, 1.0, v16
	v_add_f32_e32 v17, 1.0, v17
	v_add_f32_e32 v18, 1.0, v18
	v_add_f32_e32 v19, 1.0, v19
	v_rcp_f32_e32 v220, v16
	v_rcp_f32_e32 v221, v17
	v_rcp_f32_e32 v222, v18
	v_rcp_f32_e32 v223, v19
	v_fma_f32 v224, -v16, v220, 1.0
	v_fma_f32 v225, -v17, v221, 1.0
	v_fma_f32 v226, -v18, v222, 1.0
	v_fma_f32 v227, -v19, v223, 1.0
	v_fma_f32 v16, v224, v220, v220
	v_fma_f32 v17, v225, v221, v221
	v_fma_f32 v18, v226, v222, v222
	v_fma_f32 v19, v227, v223, v223
	v_lshlrev_b32_e32 v230, 16, v134
	v_and_b32_e32 v134, 0xffff0000, v134
	v_lshlrev_b32_e32 v231, 16, v135
	v_and_b32_e32 v135, 0xffff0000, v135
	v_lshlrev_b32_e32 v232, 16, v136
	v_and_b32_e32 v136, 0xffff0000, v136
	v_lshlrev_b32_e32 v233, 16, v137
	v_and_b32_e32 v137, 0xffff0000, v137
	v_fma_f32 v16, v16, v232, v230
	v_fma_f32 v17, v17, v136, v134
	v_fma_f32 v18, v18, v233, v231
	v_fma_f32 v19, v19, v137, v135
	global_store_dwordx4 v252, v[16:19], s[42:43] offset:576
	v_add_u32_e32 v188, 0xb0000, v140
	v_mul_f32_e32 v12, v12, v215
	v_mul_f32_e32 v13, v13, v215
	v_mul_f32_e32 v14, v14, v215
	v_mul_f32_e32 v15, v15, v215
	v_mul_f32_e32 v12, 0xbfb8aa3b, v12
	v_mul_f32_e32 v13, 0xbfb8aa3b, v13
	v_mul_f32_e32 v14, 0xbfb8aa3b, v14
	v_mul_f32_e32 v15, 0xbfb8aa3b, v15
	v_exp_f32_e32 v12, v12
	v_exp_f32_e32 v13, v13
	v_exp_f32_e32 v14, v14
	v_exp_f32_e32 v15, v15
	v_add_f32_e32 v12, 1.0, v12
	v_add_f32_e32 v13, 1.0, v13
	v_add_f32_e32 v14, 1.0, v14
	v_add_f32_e32 v15, 1.0, v15
	v_rcp_f32_e32 v220, v12
	v_rcp_f32_e32 v221, v13
	v_rcp_f32_e32 v222, v14
	v_rcp_f32_e32 v223, v15
	v_fma_f32 v224, -v12, v220, 1.0
	v_fma_f32 v225, -v13, v221, 1.0
	v_fma_f32 v226, -v14, v222, 1.0
	v_fma_f32 v227, -v15, v223, 1.0
	v_fma_f32 v12, v224, v220, v220
	v_fma_f32 v13, v225, v221, v221
	v_fma_f32 v14, v226, v222, v222
	v_fma_f32 v15, v227, v223, v223
	v_lshlrev_b32_e32 v230, 16, v138
	v_and_b32_e32 v138, 0xffff0000, v138
	v_lshlrev_b32_e32 v231, 16, v139
	v_and_b32_e32 v139, 0xffff0000, v139
	v_lshlrev_b32_e32 v232, 16, v142
	v_and_b32_e32 v142, 0xffff0000, v142
	v_lshlrev_b32_e32 v233, 16, v143
	v_and_b32_e32 v143, 0xffff0000, v143
	v_fma_f32 v12, v12, v232, v230
	v_fma_f32 v13, v13, v142, v138
	v_fma_f32 v14, v14, v233, v231
	v_fma_f32 v15, v15, v143, v139
	v_lshlrev_b32_e32 v252, 1, v188
	global_store_dwordx4 v252, v[12:15], s[42:43] offset:0
	v_mul_f32_e32 v8, v8, v215
	v_mul_f32_e32 v9, v9, v215
	v_mul_f32_e32 v10, v10, v215
	v_mul_f32_e32 v11, v11, v215
	v_mul_f32_e32 v8, 0xbfb8aa3b, v8
	v_mul_f32_e32 v9, 0xbfb8aa3b, v9
	v_mul_f32_e32 v10, 0xbfb8aa3b, v10
	v_mul_f32_e32 v11, 0xbfb8aa3b, v11
	v_exp_f32_e32 v8, v8
	v_exp_f32_e32 v9, v9
	v_exp_f32_e32 v10, v10
	v_exp_f32_e32 v11, v11
	v_add_f32_e32 v8, 1.0, v8
	v_add_f32_e32 v9, 1.0, v9
	v_add_f32_e32 v10, 1.0, v10
	v_add_f32_e32 v11, 1.0, v11
	v_rcp_f32_e32 v220, v8
	v_rcp_f32_e32 v221, v9
	v_rcp_f32_e32 v222, v10
	v_rcp_f32_e32 v223, v11
	v_fma_f32 v224, -v8, v220, 1.0
	v_fma_f32 v225, -v9, v221, 1.0
	v_fma_f32 v226, -v10, v222, 1.0
	v_fma_f32 v227, -v11, v223, 1.0
	v_fma_f32 v8, v224, v220, v220
	v_fma_f32 v9, v225, v221, v221
	v_fma_f32 v10, v226, v222, v222
	v_fma_f32 v11, v227, v223, v223
	v_lshlrev_b32_e32 v230, 16, v144
	v_and_b32_e32 v144, 0xffff0000, v144
	v_lshlrev_b32_e32 v231, 16, v145
	v_and_b32_e32 v145, 0xffff0000, v145
	v_lshlrev_b32_e32 v232, 16, v190
	v_and_b32_e32 v190, 0xffff0000, v190
	v_lshlrev_b32_e32 v233, 16, v191
	v_and_b32_e32 v191, 0xffff0000, v191
	v_fma_f32 v8, v8, v232, v230
	v_fma_f32 v9, v9, v190, v144
	v_fma_f32 v10, v10, v233, v231
	v_fma_f32 v11, v11, v191, v145
	global_store_dwordx4 v252, v[8:11], s[42:43] offset:64
	v_mul_f32_e32 v4, v4, v215
	v_mul_f32_e32 v5, v5, v215
	v_mul_f32_e32 v6, v6, v215
	v_mul_f32_e32 v7, v7, v215
	v_mul_f32_e32 v4, 0xbfb8aa3b, v4
	v_mul_f32_e32 v5, 0xbfb8aa3b, v5
	v_mul_f32_e32 v6, 0xbfb8aa3b, v6
	v_mul_f32_e32 v7, 0xbfb8aa3b, v7
	v_exp_f32_e32 v4, v4
	v_exp_f32_e32 v5, v5
	v_exp_f32_e32 v6, v6
	v_exp_f32_e32 v7, v7
	v_add_f32_e32 v4, 1.0, v4
	v_add_f32_e32 v5, 1.0, v5
	v_add_f32_e32 v6, 1.0, v6
	v_add_f32_e32 v7, 1.0, v7
	v_rcp_f32_e32 v220, v4
	v_rcp_f32_e32 v221, v5
	v_rcp_f32_e32 v222, v6
	v_rcp_f32_e32 v223, v7
	v_fma_f32 v224, -v4, v220, 1.0
	v_fma_f32 v225, -v5, v221, 1.0
	v_fma_f32 v226, -v6, v222, 1.0
	v_fma_f32 v227, -v7, v223, 1.0
	v_fma_f32 v4, v224, v220, v220
	v_fma_f32 v5, v225, v221, v221
	v_fma_f32 v6, v226, v222, v222
	v_fma_f32 v7, v227, v223, v223
	v_lshlrev_b32_e32 v230, 16, v194
	v_and_b32_e32 v194, 0xffff0000, v194
	v_lshlrev_b32_e32 v231, 16, v195
	v_and_b32_e32 v195, 0xffff0000, v195
	v_lshlrev_b32_e32 v232, 16, v248
	v_and_b32_e32 v248, 0xffff0000, v248
	v_lshlrev_b32_e32 v233, 16, v249
	v_and_b32_e32 v249, 0xffff0000, v249
	v_fma_f32 v4, v4, v232, v230
	v_fma_f32 v5, v5, v248, v194
	v_fma_f32 v6, v6, v233, v231
	v_fma_f32 v7, v7, v249, v195
	global_store_dwordx4 v252, v[4:7], s[42:43] offset:512
	v_mul_f32_e32 v0, v0, v215
	v_mul_f32_e32 v1, v1, v215
	v_mul_f32_e32 v2, v2, v215
	v_mul_f32_e32 v3, v3, v215
	v_mul_f32_e32 v0, 0xbfb8aa3b, v0
	v_mul_f32_e32 v1, 0xbfb8aa3b, v1
	v_mul_f32_e32 v2, 0xbfb8aa3b, v2
	v_mul_f32_e32 v3, 0xbfb8aa3b, v3
	v_exp_f32_e32 v0, v0
	v_exp_f32_e32 v1, v1
	v_exp_f32_e32 v2, v2
	v_exp_f32_e32 v3, v3
	v_add_f32_e32 v0, 1.0, v0
	v_add_f32_e32 v1, 1.0, v1
	v_add_f32_e32 v2, 1.0, v2
	v_add_f32_e32 v3, 1.0, v3
	v_rcp_f32_e32 v220, v0
	v_rcp_f32_e32 v221, v1
	v_rcp_f32_e32 v222, v2
	v_rcp_f32_e32 v223, v3
	v_fma_f32 v224, -v0, v220, 1.0
	v_fma_f32 v225, -v1, v221, 1.0
	v_fma_f32 v226, -v2, v222, 1.0
	v_fma_f32 v227, -v3, v223, 1.0
	v_fma_f32 v0, v224, v220, v220
	v_fma_f32 v1, v225, v221, v221
	v_fma_f32 v2, v226, v222, v222
	v_fma_f32 v3, v227, v223, v223
	v_lshlrev_b32_e32 v230, 16, v150
	v_and_b32_e32 v150, 0xffff0000, v150
	v_lshlrev_b32_e32 v231, 16, v151
	v_and_b32_e32 v151, 0xffff0000, v151
	v_lshlrev_b32_e32 v232, 16, v234
	v_and_b32_e32 v234, 0xffff0000, v234
	v_lshlrev_b32_e32 v233, 16, v235
	v_and_b32_e32 v235, 0xffff0000, v235
	v_fma_f32 v0, v0, v232, v230
	v_fma_f32 v1, v1, v234, v150
	v_fma_f32 v2, v2, v233, v231
	v_fma_f32 v3, v3, v235, v151
	global_store_dwordx4 v252, v[0:3], s[42:43] offset:576
	v_readlane_b32 s2, v255, 21
	v_readlane_b32 s3, v255, 22
	s_and_b64 vcc, exec, s[38:39]
	s_cbranch_vccz .LBB0_658
	s_waitcnt vmcnt(0)
	v_readlane_b32 s40, v255, 32
	s_mov_b32 s48, s2
	s_cmpk_gt_u32 s95, 0xff
	v_readlane_b32 s41, v255, 33
	s_cbranch_scc1 .LBB0_669
	s_barrier
